# v060 + every GEMM unit issues the LDS reads of its first load segment at the top of the unit loop, ahead of the scheduler/pointer set-up chain (all 7 GEMM phases)
# speedup vs baseline: 1.0034x; 1.0034x over previous
; #define PG8_STAGE(bufoff, gbase, voff) do { _Pragma("unroll") for (int _i = 0; _i < 2; ++_i) \
;         __builtin_amdgcn_global_load_lds((const unsigned*)((const char*)(gbase) + (voff)[_i]), (PG8_LAS unsigned*)(lds + (bufoff) + ldsw + _i * 8192), 16, 0, AUX_A); } while (0)
; #define PG8_LDA(dst, b, h) do { _Pragma("unroll") for (int m = 0; m < 4; ++m) _Pragma("unroll") for (int k = 0; k < 2; ++k) dst[m][k] = *(const PG8_LAS bf16x8*)(lds + PG8_SA(b, h) + aoff + m * 2048 + k * 1024); } while (0)
; #define PG8_LDB(dst, b, h) do { _Pragma("unroll") for (int n = 0; n < 2; ++n) _Pragma("unroll") for (int k = 0; k < 2; ++k) dst[n][k] = *(const PG8_LAS bf16x8*)(lds + PG8_SB(b, h) + boff + n * 2048 + k * 1024); } while (0)
; #define PG8_SCHED __builtin_amdgcn_sched_barrier(0)
;     __host__ __device__ bool next(int i, Unit& u) const {
;         const long L = (long)i * G + c; if (L >= nwg) return false;
;         int wgid = (int)L; { const int q = nwg / NXCD, r = nwg % NXCD, xcd = wgid % NXCD, off = wgid / NXCD; wgid = (xcd < r ? xcd * (q + 1) : r * (q + 1) + (xcd - r) * q) + off; }
;         if (ORD_TR > 0) {
;             const int nig = ORD_TR * nM, gid = wgid / nig, fn = gid * ORD_TR, gsz = (nN - fn) < ORD_TR ? (nN - fn) : ORD_TR;
;             u.pn = fn + ((wgid % nig) % gsz); u.pm = (wgid % nig) / gsz; u.kt0 = 0; u.nkt = nkt; u.slab = -1; u.krot = 0; return true; }
;         const int nig = WGM * nN, gid = wgid / nig, fm = gid * WGM, gsz = (nM - fm) < WGM ? (nM - fm) : WGM;
;         u.pm = fm + ((wgid % nig) % gsz); u.pn = (wgid % nig) / gsz; u.kt0 = 0; u.nkt = nkt; u.slab = -1; u.krot = KROT ? 2 * (((c & 7) * (nkt >> 1)) >> 3) : 0; return true;
; template <class Epi, class Sched, bool ALIGN_EPI = false, bool SP2 = false>
; __device__ __forceinline__ void gemm_phase(PG8_LAS unsigned char* lds, const Gemm g, const Sched& S, const Epi& E) {
;     ...
;             PG8_LDB(B0, 0, 0); PG8_LDB(B1, 0, 1); PG8_SCHED; PG8_LDA(At, 0, 0); PG8_STAGE(PG8_SA(1, 1), a1 + hstep, voffA);
.LBB0_924:
	v_add_u32_e32 v160, 0x10000, v99
	v_add_u32_e32 v166, 0x14000, v99
	ds_read_b128 v[22:25], v160
	ds_read_b128 v[34:37], v160 offset:1024
	ds_read_b128 v[38:41], v160 offset:2048
	ds_read_b128 v[160:163], v160 offset:3072
	ds_read_b128 v[180:183], v166
	ds_read_b128 v[184:187], v166 offset:1024
	ds_read_b128 v[188:191], v166 offset:2048
	ds_read_b128 v[192:195], v166 offset:3072
	ds_read_b128 v[196:199], v165
	ds_read_b128 v[200:203], v165 offset:1024
	ds_read_b128 v[222:225], v165 offset:2048
	ds_read_b128 v[226:229], v165 offset:3072
	ds_read_b128 v[230:233], v165 offset:4096
	ds_read_b128 v[234:237], v165 offset:5120
	ds_read_b128 v[238:241], v165 offset:6144
	ds_read_b128 v[242:245], v165 offset:7168
	s_add_i32 s75, s75, 1
	s_and_b64 vcc, exec, s[36:37]
	s_mov_b64 s[38:39], -1
	s_cbranch_vccnz .LBB0_927
	v_readlane_b32 s0, v251, 56
	s_mul_i32 s0, s75, s0
	s_mul_hi_u32 s1, s75, s68
	s_add_i32 s1, s1, s0
	s_mul_i32 s0, s75, s68
	s_add_u32 s40, s0, s92
	v_readlane_b32 s0, v251, 55
	s_addc_u32 s41, s1, s0
	v_mov_b64_e32 v[2:3], 0x8f
	v_cmp_gt_i64_e32 vcc, s[40:41], v[2:3]
	s_mov_b64 s[38:39], 0
	s_mov_b64 s[18:19], 0
	s_mov_b32 s1, s14
	s_mov_b32 s0, s16
	s_cbranch_vccnz .LBB0_927
	s_ashr_i32 s0, s40, 31
	s_lshr_b32 s0, s0, 29
	s_add_i32 s0, s40, s0
	s_ashr_i32 s1, s0, 3
	s_and_b32 s0, s0, -8
	s_sub_i32 s0, s40, s0
	s_cmp_lt_i32 s0, 0
	s_cselect_b32 s2, 19, 18
	s_mul_i32 s0, s0, s2
	s_add_i32 s0, s0, s1
	s_mul_hi_i32 s1, s0, 0x2aaaaaab
	s_lshr_b32 s2, s1, 31
	s_ashr_i32 s1, s1, 2
	s_add_i32 s1, s1, s2
	s_mul_i32 s2, s1, 6
	s_sub_i32 s15, 36, s2
	s_min_i32 s15, s15, 6
	s_abs_i32 s17, s15
	v_cvt_f32_u32_e32 v2, s17
	s_sub_i32 s19, 0, s17
	s_mul_i32 s1, s1, 24
	s_sub_i32 s1, s0, s1
	v_rcp_iflag_f32_e32 v2, v2
	s_abs_i32 s0, s1
	s_xor_b32 s18, s1, s15
	s_ashr_i32 s18, s18, 31
	v_mul_f32_e32 v2, 0x4f7ffffe, v2
	v_cvt_u32_f32_e32 v2, v2
	s_nop 0
	v_readfirstlane_b32 s29, v2
	s_mul_i32 s19, s19, s29
	s_mul_hi_u32 s19, s29, s19
	s_add_i32 s29, s29, s19
	s_mul_hi_u32 s19, s0, s29
	s_mul_i32 s29, s19, s17
	s_sub_i32 s0, s0, s29
	s_add_i32 s40, s19, 1
	s_sub_i32 s29, s0, s17
	s_cmp_ge_u32 s0, s17
	s_cselect_b32 s19, s40, s19
	s_cselect_b32 s0, s29, s0
	s_add_i32 s29, s19, 1
	s_cmp_ge_u32 s0, s17
	s_cselect_b32 s0, s29, s19
	s_xor_b32 s0, s0, s18
	s_sub_i32 s0, s0, s18
	s_mul_i32 s15, s0, s15
	s_sub_i32 s1, s1, s15
	s_add_i32 s1, s2, s1
	s_mov_b64 s[18:19], -1

; #define PG8_STAGE(bufoff, gbase, voff) do { _Pragma("unroll") for (int _i = 0; _i < 2; ++_i) \
;         __builtin_amdgcn_global_load_lds((const unsigned*)((const char*)(gbase) + (voff)[_i]), (PG8_LAS unsigned*)(lds + (bufoff) + ldsw + _i * 8192), 16, 0, AUX_A); } while (0)
; #define PG8_STAGEB(bufoff, gbase, voff) do { _Pragma("unroll") for (int _i = 0; _i < 2; ++_i) \
;         __builtin_amdgcn_global_load_lds((const unsigned*)((const char*)(gbase) + (voff)[_i]), (PG8_LAS unsigned*)(lds + (bufoff) + ldsw + _i * 8192), 16, 0, AUX_B); } while (0)
; #define PG8_LDA(dst, b, h) do { _Pragma("unroll") for (int m = 0; m < 4; ++m) _Pragma("unroll") for (int k = 0; k < 2; ++k) dst[m][k] = *(const PG8_LAS bf16x8*)(lds + PG8_SA(b, h) + aoff + m * 2048 + k * 1024); } while (0)
; #define PG8_LDB(dst, b, h) do { _Pragma("unroll") for (int n = 0; n < 2; ++n) _Pragma("unroll") for (int k = 0; k < 2; ++k) dst[n][k] = *(const PG8_LAS bf16x8*)(lds + PG8_SB(b, h) + boff + n * 2048 + k * 1024); } while (0)
; #define PG8_MMA(ai, bj, At, Bt) do { __builtin_amdgcn_s_setprio(1); _Pragma("unroll") for (int m = 0; m < 4; ++m) _Pragma("unroll") for (int n = 0; n < 2; ++n) _Pragma("unroll") for (int k = 0; k < 2; ++k) \
;         acc[ai][bj][m][n] = __builtin_amdgcn_mfma_f32_16x16x32_bf16(Bt[n][k], At[m][k], acc[ai][bj][m][n], 0, 0, 0); __builtin_amdgcn_s_setprio(0); } while (0)
; #define PG8_WAIT_V(n) asm volatile("s_waitcnt vmcnt(" #n ")" ::: "memory")
; #define PG8_WAIT_L(n) asm volatile("s_waitcnt lgkmcnt(" #n ")" ::: "memory")
; #define PG8_BAR __builtin_amdgcn_s_barrier()
; #define PG8_SCHED __builtin_amdgcn_sched_barrier(0)
; template <class Epi, class Sched, bool ALIGN_EPI = false, bool SP2 = false>
; __device__ __forceinline__ void gemm_phase(PG8_LAS unsigned char* lds, const Gemm g, const Sched& S, const Epi& E) {
;     ...
;             PG8_LDB(B0, 0, 0); PG8_LDB(B1, 0, 1); PG8_SCHED; PG8_LDA(At, 0, 0); PG8_STAGE(PG8_SA(1, 1), a1 + hstep, voffA);
;             PG8_WAIT_V(8); PG8_WAIT_L(0); PG8_BAR; PG8_MMA(0, 0, At, B0); PG8_MMA(0, 1, At, B1); PG8_BAR; PG8_SCHED;
;             PG8_LDA(At, 0, 1); PG8_STAGEB(PG8_SB(0, 0), b2, voffB); PG8_STAGEB(PG8_SB(0, 1), b2 + hstep, voffB); PG8_STAGE(PG8_SA(0, 0), a2, voffA);
;             PG8_WAIT_V(8); PG8_WAIT_L(0); PG8_BAR; PG8_MMA(1, 0, At, B0); PG8_MMA(1, 1, At, B1); PG8_BAR; PG8_SCHED;
.Lrp_936:
.Lpk_936:
	s_add_i32 s81, s29, 2
	s_cmp_lt_u32 s29, 14
	s_cselect_b32 s0, 0, -16
	s_add_i32 s0, s81, s0
	s_ashr_i32 s1, s0, 31
	s_lshl_b64 s[0:1], s[0:1], 7
	s_add_u32 s2, s64, s0
	s_addc_u32 s46, s65, s1
	s_add_u32 s0, s26, s0
	s_addc_u32 s1, s27, s1
	s_cmp_eq_u32 s29, 14
	s_cselect_b32 s57, s15, s46
	s_cselect_b32 s56, s17, s2
	s_cselect_b32 s59, s43, s1
	s_cselect_b32 s58, s78, s0
	s_add_i32 s2, 0, 0x10000
	s_add_i32 s83, s2, s33
	s_add_i32 s46, 0, 0x14000
	s_add_i32 m0, s25, 0xc000
	s_add_i32 s82, s25, 0xe000
	s_add_i32 s84, s83, 0x2000
	s_add_u32 s60, s58, 0x40000
	s_addc_u32 s61, s59, 0
	s_add_i32 s88, s46, s33
	s_add_i32 s89, s88, 0x2000
	s_add_i32 s90, 0, 0x18000
	s_add_i32 s91, 0, 0x1c000
	s_add_u32 s54, s56, 0x40000
	s_addc_u32 s55, s57, 0
	s_add_i32 s1, s90, s33
	s_add_i32 s0, s1, 0x2000
	s_add_u32 s52, s58, 0x40080
	s_addc_u32 s53, s59, 0
	s_add_i32 s47, s91, s33
	s_add_i32 s46, s47, 0x2000
	s_cmp_gt_u32 s29, 13
	global_load_lds_dwordx4 v[16:17], off
	s_mov_b32 m0, s82
	s_nop 0
	global_load_lds_dwordx4 v[14:15], off
	s_waitcnt vmcnt(8)
	s_waitcnt lgkmcnt(0)
	s_setprio 1
	s_barrier
	v_mfma_f32_16x16x32_bf16 v[144:147], v[22:25], v[196:199], 0
	v_mfma_f32_16x16x32_bf16 v[144:147], v[34:37], v[200:203], v[144:147]
	v_mfma_f32_16x16x32_bf16 v[140:143], v[38:41], v[196:199], 0
	v_mfma_f32_16x16x32_bf16 v[140:143], v[160:163], v[200:203], v[140:143]
	v_mfma_f32_16x16x32_bf16 v[128:131], v[22:25], v[222:225], 0
	v_mfma_f32_16x16x32_bf16 v[128:131], v[34:37], v[226:229], v[128:131]
	v_mfma_f32_16x16x32_bf16 v[124:127], v[38:41], v[222:225], 0
	v_mfma_f32_16x16x32_bf16 v[124:127], v[160:163], v[226:229], v[124:127]
	v_mfma_f32_16x16x32_bf16 v[112:115], v[22:25], v[230:233], 0
	v_mfma_f32_16x16x32_bf16 v[112:115], v[34:37], v[234:237], v[112:115]
	v_mfma_f32_16x16x32_bf16 v[108:111], v[38:41], v[230:233], 0
	v_mfma_f32_16x16x32_bf16 v[108:111], v[160:163], v[234:237], v[108:111]
	v_mfma_f32_16x16x32_bf16 v[94:97], v[22:25], v[238:241], 0
	v_mfma_f32_16x16x32_bf16 v[94:97], v[34:37], v[242:245], v[94:97]
	v_mfma_f32_16x16x32_bf16 v[90:93], v[38:41], v[238:241], 0
	v_mfma_f32_16x16x32_bf16 v[90:93], v[160:163], v[242:245], v[90:93]
	s_setprio 0
	s_setprio 1
	v_mfma_f32_16x16x32_bf16 v[136:139], v[180:183], v[196:199], 0
	v_mfma_f32_16x16x32_bf16 v[136:139], v[184:187], v[200:203], v[136:139]
	v_mfma_f32_16x16x32_bf16 v[132:135], v[188:191], v[196:199], 0
	v_mfma_f32_16x16x32_bf16 v[132:135], v[192:195], v[200:203], v[132:135]
	v_mfma_f32_16x16x32_bf16 v[120:123], v[180:183], v[222:225], 0
	v_mfma_f32_16x16x32_bf16 v[120:123], v[184:187], v[226:229], v[120:123]
	v_mfma_f32_16x16x32_bf16 v[116:119], v[188:191], v[222:225], 0
	v_mfma_f32_16x16x32_bf16 v[116:119], v[192:195], v[226:229], v[116:119]
	v_mfma_f32_16x16x32_bf16 v[104:107], v[180:183], v[230:233], 0
	v_mfma_f32_16x16x32_bf16 v[104:107], v[184:187], v[234:237], v[104:107]
	v_mfma_f32_16x16x32_bf16 v[100:103], v[188:191], v[230:233], 0
	v_mfma_f32_16x16x32_bf16 v[100:103], v[192:195], v[234:237], v[100:103]
	v_mfma_f32_16x16x32_bf16 v[86:89], v[180:183], v[238:241], 0
	v_mfma_f32_16x16x32_bf16 v[86:89], v[184:187], v[242:245], v[86:89]
	s_setprio 2
	s_barrier
	v_mfma_f32_16x16x32_bf16 v[82:85], v[188:191], v[238:241], 0
	v_mfma_f32_16x16x32_bf16 v[82:85], v[192:195], v[242:245], v[82:85]
	s_setprio 0
	s_mov_b32 m0, s83
	v_lshl_add_u64 v[166:167], s[58:59], 0, v[150:151]
	ds_read_b128 v[196:199], v165 offset:16384
	ds_read_b128 v[200:203], v165 offset:17408
	ds_read_b128 v[222:225], v165 offset:18432
	ds_read_b128 v[226:229], v165 offset:19456
	ds_read_b128 v[230:233], v165 offset:20480
	ds_read_b128 v[234:237], v165 offset:21504
	ds_read_b128 v[238:241], v165 offset:22528
	ds_read_b128 v[242:245], v165 offset:23552
	global_load_lds_dwordx4 v[166:167], off
	v_lshl_add_u64 v[168:169], s[58:59], 0, v[154:155]
	s_mov_b32 m0, s84
	v_lshl_add_u64 v[172:173], s[60:61], 0, v[150:151]
	global_load_lds_dwordx4 v[168:169], off
	s_mov_b32 m0, s88
	v_lshl_add_u64 v[212:213], s[56:57], 0, v[152:153]
	global_load_lds_dwordx4 v[172:173], off
	v_lshl_add_u64 v[172:173], s[60:61], 0, v[154:155]
	s_mov_b32 m0, s89
	s_nop 0
	global_load_lds_dwordx4 v[172:173], off
	v_lshl_add_u64 v[172:173], s[56:57], 0, v[148:149]
	s_mov_b32 m0, s25
	s_nop 0
	global_load_lds_dwordx4 v[172:173], off
	s_mov_b32 m0, s62
	s_nop 0
	global_load_lds_dwordx4 v[212:213], off
	s_waitcnt vmcnt(8)
	s_waitcnt lgkmcnt(0)
	s_setprio 1
	s_barrier
	v_mfma_f32_16x16x32_bf16 v[78:81], v[22:25], v[196:199], 0
	v_mfma_f32_16x16x32_bf16 v[78:81], v[34:37], v[200:203], v[78:81]
	v_mfma_f32_16x16x32_bf16 v[74:77], v[38:41], v[196:199], 0
	v_mfma_f32_16x16x32_bf16 v[74:77], v[160:163], v[200:203], v[74:77]
	v_mfma_f32_16x16x32_bf16 v[62:65], v[22:25], v[222:225], 0
	v_mfma_f32_16x16x32_bf16 v[62:65], v[34:37], v[226:229], v[62:65]
	v_mfma_f32_16x16x32_bf16 v[58:61], v[38:41], v[222:225], 0
	v_mfma_f32_16x16x32_bf16 v[58:61], v[160:163], v[226:229], v[58:61]
	v_mfma_f32_16x16x32_bf16 v[46:49], v[22:25], v[230:233], 0
	v_mfma_f32_16x16x32_bf16 v[46:49], v[34:37], v[234:237], v[46:49]
	v_mfma_f32_16x16x32_bf16 v[42:45], v[38:41], v[230:233], 0
	v_mfma_f32_16x16x32_bf16 v[42:45], v[160:163], v[234:237], v[42:45]
	v_mfma_f32_16x16x32_bf16 v[18:21], v[22:25], v[238:241], 0
	v_mfma_f32_16x16x32_bf16 v[18:21], v[34:37], v[242:245], v[18:21]
	v_mfma_f32_16x16x32_bf16 v[10:13], v[38:41], v[238:241], 0
	v_mfma_f32_16x16x32_bf16 v[10:13], v[160:163], v[242:245], v[10:13]
	s_setprio 0
	s_setprio 1
	v_mfma_f32_16x16x32_bf16 v[50:53], v[188:191], v[222:225], 0
	v_mfma_f32_16x16x32_bf16 v[30:33], v[180:183], v[230:233], 0
	v_mfma_f32_16x16x32_bf16 v[26:29], v[188:191], v[230:233], 0
	v_mfma_f32_16x16x32_bf16 v[6:9], v[180:183], v[238:241], 0
	v_mfma_f32_16x16x32_bf16 v[2:5], v[188:191], v[238:241], 0
	v_mfma_f32_16x16x32_bf16 v[22:25], v[180:183], v[196:199], 0
	v_mfma_f32_16x16x32_bf16 v[34:37], v[188:191], v[196:199], 0
	v_mfma_f32_16x16x32_bf16 v[38:41], v[180:183], v[222:225], 0
	v_mfma_f32_16x16x32_bf16 v[50:53], v[192:195], v[226:229], v[50:53]
	v_mfma_f32_16x16x32_bf16 v[30:33], v[184:187], v[234:237], v[30:33]
	v_mfma_f32_16x16x32_bf16 v[26:29], v[192:195], v[234:237], v[26:29]
	v_mfma_f32_16x16x32_bf16 v[6:9], v[184:187], v[242:245], v[6:9]
	v_mfma_f32_16x16x32_bf16 v[2:5], v[192:195], v[242:245], v[2:5]
	v_mfma_f32_16x16x32_bf16 v[22:25], v[184:187], v[200:203], v[22:25]
	s_setprio 2
	s_barrier
; #define PG8_STAGE(bufoff, gbase, voff) do { _Pragma("unroll") for (int _i = 0; _i < 2; ++_i) \
;         __builtin_amdgcn_global_load_lds((const unsigned*)((const char*)(gbase) + (voff)[_i]), (PG8_LAS unsigned*)(lds + (bufoff) + ldsw + _i * 8192), 16, 0, AUX_A); } while (0)
; #define PG8_STAGEB(bufoff, gbase, voff) do { _Pragma("unroll") for (int _i = 0; _i < 2; ++_i) \
;         __builtin_amdgcn_global_load_lds((const unsigned*)((const char*)(gbase) + (voff)[_i]), (PG8_LAS unsigned*)(lds + (bufoff) + ldsw + _i * 8192), 16, 0, AUX_B); } while (0)
; #define PG8_LDA(dst, b, h) do { _Pragma("unroll") for (int m = 0; m < 4; ++m) _Pragma("unroll") for (int k = 0; k < 2; ++k) dst[m][k] = *(const PG8_LAS bf16x8*)(lds + PG8_SA(b, h) + aoff + m * 2048 + k * 1024); } while (0)
; #define PG8_LDB(dst, b, h) do { _Pragma("unroll") for (int n = 0; n < 2; ++n) _Pragma("unroll") for (int k = 0; k < 2; ++k) dst[n][k] = *(const PG8_LAS bf16x8*)(lds + PG8_SB(b, h) + boff + n * 2048 + k * 1024); } while (0)
; #define PG8_MMA(ai, bj, At, Bt) do { __builtin_amdgcn_s_setprio(1); _Pragma("unroll") for (int m = 0; m < 4; ++m) _Pragma("unroll") for (int n = 0; n < 2; ++n) _Pragma("unroll") for (int k = 0; k < 2; ++k) \
;         acc[ai][bj][m][n] = __builtin_amdgcn_mfma_f32_16x16x32_bf16(Bt[n][k], At[m][k], acc[ai][bj][m][n], 0, 0, 0); __builtin_amdgcn_s_setprio(0); } while (0)
; #define PG8_WAIT_V(n) asm volatile("s_waitcnt vmcnt(" #n ")" ::: "memory")
; #define PG8_WAIT_L(n) asm volatile("s_waitcnt lgkmcnt(" #n ")" ::: "memory")
; #define PG8_BAR __builtin_amdgcn_s_barrier()
; #define PG8_SCHED __builtin_amdgcn_sched_barrier(0)
; template <class Epi, class Sched, bool ALIGN_EPI = false, bool SP2 = false>
; __device__ __forceinline__ void gemm_phase(PG8_LAS unsigned char* lds, const Gemm g, const Sched& S, const Epi& E) {
;     ...
;             PG8_LDB(B0, 1, 0); PG8_LDB(B1, 1, 1); PG8_SCHED; PG8_LDA(At, 1, 0); PG8_STAGE(PG8_SA(0, 1), a2 + hstep, voffA);
;             PG8_WAIT_V(8); PG8_WAIT_L(0); PG8_BAR; PG8_MMA(0, 0, At, B0); PG8_MMA(0, 1, At, B1); PG8_BAR; PG8_SCHED;
;             PG8_LDA(At, 1, 1); PG8_STAGEB(PG8_SB(1, 0), b3, voffB); PG8_STAGEB(PG8_SB(1, 1), b3 + hstep, voffB); PG8_STAGE(PG8_SA(1, 0), a3, voffA);
;             PG8_WAIT_V(8); PG8_WAIT_L(0); PG8_BAR; PG8_MMA(1, 0, At, B0); PG8_MMA(1, 1, At, B1); PG8_BAR; PG8_SCHED;
	v_mfma_f32_16x16x32_bf16 v[34:37], v[192:195], v[200:203], v[34:37]
	v_mfma_f32_16x16x32_bf16 v[38:41], v[184:187], v[226:229], v[38:41]
	s_setprio 0
	v_add_u32_e32 v160, s90, v99
	v_add_u32_e32 v192, s91, v99
	ds_read_b128 v[54:57], v160
	ds_read_b128 v[66:69], v160 offset:1024
	ds_read_b128 v[70:73], v160 offset:2048
	ds_read_b128 v[160:163], v160 offset:3072
	ds_read_b128 v[180:183], v192
	ds_read_b128 v[184:187], v192 offset:1024
	ds_read_b128 v[188:191], v192 offset:2048
	ds_read_b128 v[192:195], v192 offset:3072
	s_mov_b32 m0, s63
	v_lshl_add_u64 v[246:247], s[54:55], 0, v[148:149]
	ds_read_b128 v[196:199], v165 offset:32768
	ds_read_b128 v[200:203], v165 offset:33792
	ds_read_b128 v[222:225], v165 offset:34816
	ds_read_b128 v[226:229], v165 offset:35840
	ds_read_b128 v[230:233], v165 offset:36864
	ds_read_b128 v[234:237], v165 offset:37888
	ds_read_b128 v[238:241], v165 offset:38912
	ds_read_b128 v[242:245], v165 offset:39936
	global_load_lds_dwordx4 v[246:247], off
	v_lshl_add_u64 v[246:247], s[54:55], 0, v[152:153]
	s_mov_b32 m0, s69
	s_nop 0
	global_load_lds_dwordx4 v[246:247], off
	s_waitcnt vmcnt(8)
	s_waitcnt lgkmcnt(0)
	s_setprio 1
	s_barrier
	v_mfma_f32_16x16x32_bf16 v[144:147], v[54:57], v[196:199], v[144:147]
	v_mfma_f32_16x16x32_bf16 v[144:147], v[66:69], v[200:203], v[144:147]
	v_mfma_f32_16x16x32_bf16 v[140:143], v[70:73], v[196:199], v[140:143]
	v_mfma_f32_16x16x32_bf16 v[140:143], v[160:163], v[200:203], v[140:143]
	v_mfma_f32_16x16x32_bf16 v[128:131], v[54:57], v[222:225], v[128:131]
	v_mfma_f32_16x16x32_bf16 v[128:131], v[66:69], v[226:229], v[128:131]
	v_mfma_f32_16x16x32_bf16 v[124:127], v[70:73], v[222:225], v[124:127]
	v_mfma_f32_16x16x32_bf16 v[124:127], v[160:163], v[226:229], v[124:127]
	v_mfma_f32_16x16x32_bf16 v[112:115], v[54:57], v[230:233], v[112:115]
	v_mfma_f32_16x16x32_bf16 v[112:115], v[66:69], v[234:237], v[112:115]
	v_mfma_f32_16x16x32_bf16 v[108:111], v[70:73], v[230:233], v[108:111]
	v_mfma_f32_16x16x32_bf16 v[108:111], v[160:163], v[234:237], v[108:111]
	v_mfma_f32_16x16x32_bf16 v[94:97], v[54:57], v[238:241], v[94:97]
	v_mfma_f32_16x16x32_bf16 v[94:97], v[66:69], v[242:245], v[94:97]
	v_mfma_f32_16x16x32_bf16 v[90:93], v[70:73], v[238:241], v[90:93]
	v_mfma_f32_16x16x32_bf16 v[90:93], v[160:163], v[242:245], v[90:93]
	s_setprio 0
	s_setprio 1
	v_mfma_f32_16x16x32_bf16 v[136:139], v[180:183], v[196:199], v[136:139]
	v_mfma_f32_16x16x32_bf16 v[136:139], v[184:187], v[200:203], v[136:139]
	v_mfma_f32_16x16x32_bf16 v[132:135], v[188:191], v[196:199], v[132:135]
	v_mfma_f32_16x16x32_bf16 v[132:135], v[192:195], v[200:203], v[132:135]
	v_mfma_f32_16x16x32_bf16 v[120:123], v[180:183], v[222:225], v[120:123]
	v_mfma_f32_16x16x32_bf16 v[120:123], v[184:187], v[226:229], v[120:123]
	v_mfma_f32_16x16x32_bf16 v[116:119], v[188:191], v[222:225], v[116:119]
	v_mfma_f32_16x16x32_bf16 v[116:119], v[192:195], v[226:229], v[116:119]
	v_mfma_f32_16x16x32_bf16 v[104:107], v[180:183], v[230:233], v[104:107]
	v_mfma_f32_16x16x32_bf16 v[104:107], v[184:187], v[234:237], v[104:107]
	v_mfma_f32_16x16x32_bf16 v[100:103], v[188:191], v[230:233], v[100:103]
	v_mfma_f32_16x16x32_bf16 v[100:103], v[192:195], v[234:237], v[100:103]
	v_mfma_f32_16x16x32_bf16 v[86:89], v[180:183], v[238:241], v[86:89]
	v_mfma_f32_16x16x32_bf16 v[86:89], v[184:187], v[242:245], v[86:89]
	s_setprio 2
	s_barrier
	v_mfma_f32_16x16x32_bf16 v[82:85], v[188:191], v[238:241], v[82:85]
	v_mfma_f32_16x16x32_bf16 v[82:85], v[192:195], v[242:245], v[82:85]
	s_setprio 0
	s_mov_b32 m0, s1
	v_lshl_add_u64 v[166:167], v[166:167], 0, s[76:77]
	ds_read_b128 v[196:199], v165 offset:49152
	ds_read_b128 v[200:203], v165 offset:50176
	ds_read_b128 v[222:225], v165 offset:51200
	ds_read_b128 v[226:229], v165 offset:52224
	ds_read_b128 v[230:233], v165 offset:53248
	ds_read_b128 v[234:237], v165 offset:54272
	ds_read_b128 v[238:241], v165 offset:55296
	ds_read_b128 v[242:245], v165 offset:56320
	global_load_lds_dwordx4 v[166:167], off
	v_lshl_add_u64 v[166:167], v[168:169], 0, s[76:77]
	s_mov_b32 m0, s0
	s_nop 0
	global_load_lds_dwordx4 v[166:167], off
	v_lshl_add_u64 v[166:167], s[52:53], 0, v[150:151]
	s_mov_b32 m0, s47
	s_nop 0
	global_load_lds_dwordx4 v[166:167], off
	v_lshl_add_u64 v[166:167], s[52:53], 0, v[154:155]
	s_mov_b32 m0, s46
	s_nop 0
	global_load_lds_dwordx4 v[166:167], off
	v_lshl_add_u64 v[166:167], v[172:173], 0, s[76:77]
	s_mov_b32 m0, s70
	s_nop 0
	global_load_lds_dwordx4 v[166:167], off
	v_lshl_add_u64 v[166:167], v[212:213], 0, s[76:77]
	s_mov_b32 m0, s71
	s_nop 0
	global_load_lds_dwordx4 v[166:167], off
	s_waitcnt vmcnt(8)
	s_waitcnt lgkmcnt(0)
	s_setprio 1
	s_barrier
	v_mfma_f32_16x16x32_bf16 v[78:81], v[54:57], v[196:199], v[78:81]
	v_mfma_f32_16x16x32_bf16 v[78:81], v[66:69], v[200:203], v[78:81]
	v_mfma_f32_16x16x32_bf16 v[74:77], v[70:73], v[196:199], v[74:77]
	v_mfma_f32_16x16x32_bf16 v[74:77], v[160:163], v[200:203], v[74:77]
	v_mfma_f32_16x16x32_bf16 v[62:65], v[54:57], v[222:225], v[62:65]
	v_mfma_f32_16x16x32_bf16 v[62:65], v[66:69], v[226:229], v[62:65]
	v_mfma_f32_16x16x32_bf16 v[58:61], v[70:73], v[222:225], v[58:61]
	v_mfma_f32_16x16x32_bf16 v[58:61], v[160:163], v[226:229], v[58:61]
	v_mfma_f32_16x16x32_bf16 v[46:49], v[54:57], v[230:233], v[46:49]
	v_mfma_f32_16x16x32_bf16 v[46:49], v[66:69], v[234:237], v[46:49]
	v_mfma_f32_16x16x32_bf16 v[42:45], v[70:73], v[230:233], v[42:45]
	v_mfma_f32_16x16x32_bf16 v[42:45], v[160:163], v[234:237], v[42:45]
	v_mfma_f32_16x16x32_bf16 v[18:21], v[54:57], v[238:241], v[18:21]
	v_mfma_f32_16x16x32_bf16 v[18:21], v[66:69], v[242:245], v[18:21]
	v_mfma_f32_16x16x32_bf16 v[10:13], v[70:73], v[238:241], v[10:13]
	v_mfma_f32_16x16x32_bf16 v[10:13], v[160:163], v[242:245], v[10:13]
	s_setprio 0
	s_setprio 1
	v_mfma_f32_16x16x32_bf16 v[22:25], v[180:183], v[196:199], v[22:25]
	v_mfma_f32_16x16x32_bf16 v[70:73], v[184:187], v[200:203], v[22:25]
	v_mfma_f32_16x16x32_bf16 v[22:25], v[188:191], v[196:199], v[34:37]
	v_mfma_f32_16x16x32_bf16 v[66:69], v[192:195], v[200:203], v[22:25]
	v_mfma_f32_16x16x32_bf16 v[22:25], v[180:183], v[222:225], v[38:41]
	v_mfma_f32_16x16x32_bf16 v[54:57], v[184:187], v[226:229], v[22:25]
	v_mfma_f32_16x16x32_bf16 v[22:25], v[188:191], v[222:225], v[50:53]
	v_mfma_f32_16x16x32_bf16 v[50:53], v[192:195], v[226:229], v[22:25]
	v_mfma_f32_16x16x32_bf16 v[22:25], v[180:183], v[230:233], v[30:33]
	v_mfma_f32_16x16x32_bf16 v[30:33], v[184:187], v[234:237], v[22:25]
	v_mfma_f32_16x16x32_bf16 v[22:25], v[188:191], v[230:233], v[26:29]
	v_mfma_f32_16x16x32_bf16 v[6:9], v[180:183], v[238:241], v[6:9]
	v_mfma_f32_16x16x32_bf16 v[2:5], v[188:191], v[238:241], v[2:5]
	v_mfma_f32_16x16x32_bf16 v[26:29], v[192:195], v[234:237], v[22:25]
	s_setprio 2
	s_barrier
	v_mfma_f32_16x16x32_bf16 v[6:9], v[184:187], v[242:245], v[6:9]
	v_mfma_f32_16x16x32_bf16 v[2:5], v[192:195], v[242:245], v[2:5]
	s_setprio 0
	v_lshl_add_u64 v[14:15], v[14:15], 0, s[86:87]
	v_lshl_add_u64 v[16:17], v[16:17], 0, s[86:87]
	s_mov_b32 s29, s81
	s_cbranch_scc1 .Lpx_936

; #define PG8_STAGE(bufoff, gbase, voff) do { _Pragma("unroll") for (int _i = 0; _i < 2; ++_i) \
;         __builtin_amdgcn_global_load_lds((const unsigned*)((const char*)(gbase) + (voff)[_i]), (PG8_LAS unsigned*)(lds + (bufoff) + ldsw + _i * 8192), 16, 0, AUX_A); } while (0)
; #define PG8_LDA(dst, b, h) do { _Pragma("unroll") for (int m = 0; m < 4; ++m) _Pragma("unroll") for (int k = 0; k < 2; ++k) dst[m][k] = *(const PG8_LAS bf16x8*)(lds + PG8_SA(b, h) + aoff + m * 2048 + k * 1024); } while (0)
; #define PG8_LDB(dst, b, h) do { _Pragma("unroll") for (int n = 0; n < 2; ++n) _Pragma("unroll") for (int k = 0; k < 2; ++k) dst[n][k] = *(const PG8_LAS bf16x8*)(lds + PG8_SB(b, h) + boff + n * 2048 + k * 1024); } while (0)
; #define PG8_SCHED __builtin_amdgcn_sched_barrier(0)
;     __host__ __device__ bool next(int i, Unit& u) const {
;         const long L = (long)i * G + c; if (L >= nwg) return false;
;         int wgid = (int)L; { const int q = nwg / NXCD, r = nwg % NXCD, xcd = wgid % NXCD, off = wgid / NXCD; wgid = (xcd < r ? xcd * (q + 1) : r * (q + 1) + (xcd - r) * q) + off; }
;         if (ORD_TR > 0) {
;             const int nig = ORD_TR * nM, gid = wgid / nig, fn = gid * ORD_TR, gsz = (nN - fn) < ORD_TR ? (nN - fn) : ORD_TR;
;             u.pn = fn + ((wgid % nig) % gsz); u.pm = (wgid % nig) / gsz; u.kt0 = 0; u.nkt = nkt; u.slab = -1; u.krot = 0; return true; }
;         const int nig = WGM * nN, gid = wgid / nig, fm = gid * WGM, gsz = (nM - fm) < WGM ? (nM - fm) : WGM;
;         u.pm = fm + ((wgid % nig) % gsz); u.pn = (wgid % nig) / gsz; u.kt0 = 0; u.nkt = nkt; u.slab = -1; u.krot = KROT ? 2 * (((c & 7) * (nkt >> 1)) >> 3) : 0; return true;
; template <class Epi, class Sched, bool ALIGN_EPI = false, bool SP2 = false>
; __device__ __forceinline__ void gemm_phase(PG8_LAS unsigned char* lds, const Gemm g, const Sched& S, const Epi& E) {
;     ...
;             PG8_LDB(B0, 0, 0); PG8_LDB(B1, 0, 1); PG8_SCHED; PG8_LDA(At, 0, 0); PG8_STAGE(PG8_SA(1, 1), a1 + hstep, voffA);
.LBB0_1059:
	v_add_u32_e32 v148, 0x10000, v99
	ds_read_b128 v[152:155], v148
	ds_read_b128 v[156:159], v148 offset:1024
	ds_read_b128 v[160:163], v148 offset:2048
	ds_read_b128 v[164:167], v148 offset:3072
	v_add_u32_e32 v148, 0x14000, v99
	ds_read_b128 v[180:183], v148
	ds_read_b128 v[184:187], v148 offset:1024
	ds_read_b128 v[188:191], v148 offset:2048
	ds_read_b128 v[192:195], v148 offset:3072
	ds_read_b128 v[196:199], v151
	ds_read_b128 v[200:203], v151 offset:1024
	ds_read_b128 v[222:225], v151 offset:2048
	ds_read_b128 v[226:229], v151 offset:3072
	ds_read_b128 v[230:233], v151 offset:4096
	ds_read_b128 v[234:237], v151 offset:5120
	ds_read_b128 v[238:241], v151 offset:6144
	ds_read_b128 v[242:245], v151 offset:7168
	s_add_i32 s89, s0, 1
	s_and_b64 vcc, exec, s[36:37]
	s_mov_b64 s[48:49], -1
	s_cbranch_vccnz .LBB0_1062
	v_readlane_b32 s1, v251, 56
	s_mul_i32 s1, s89, s1
	s_mul_hi_u32 s2, s89, s68
	s_add_i32 s2, s2, s1
	s_mul_i32 s1, s89, s68
	s_add_u32 s50, s1, s92
	v_readlane_b32 s1, v251, 55
	s_addc_u32 s51, s2, s1
	v_cmp_gt_i64_e32 vcc, s[50:51], v[174:175]
	s_mov_b64 s[48:49], 0
	s_mov_b64 s[18:19], 0
	s_mov_b32 s15, s14
	s_mov_b32 s1, s16
	s_cbranch_vccnz .LBB0_1062
	s_ashr_i32 s1, s50, 31
	s_lshr_b32 s1, s1, 29
	s_add_i32 s1, s50, s1
	s_ashr_i32 s2, s1, 3
	s_and_b32 s1, s1, -8
	s_sub_i32 s1, s50, s1
	s_cmp_lt_i32 s1, 0
	s_cselect_b32 s15, 37, 36
	s_mul_i32 s1, s1, s15
	s_add_i32 s1, s1, s2
	s_mul_hi_i32 s2, s1, 0x2aaaaaab
	s_lshr_b32 s15, s2, 31
	s_ashr_i32 s2, s2, 3
	s_add_i32 s2, s2, s15
	s_mul_i32 s15, s2, 6
	s_sub_i32 s17, 36, s15
	s_min_i32 s17, s17, 6
	s_abs_i32 s18, s17
	v_cvt_f32_u32_e32 v2, s18
	s_sub_i32 s29, 0, s18
	s_mul_i32 s2, s2, 48
	s_sub_i32 s2, s1, s2
	v_rcp_iflag_f32_e32 v2, v2
	s_abs_i32 s1, s2
	s_xor_b32 s19, s2, s17
	s_ashr_i32 s19, s19, 31
	v_mul_f32_e32 v2, 0x4f7ffffe, v2
	v_cvt_u32_f32_e32 v2, v2
	s_nop 0
	v_readfirstlane_b32 s46, v2
	s_mul_i32 s29, s29, s46
	s_mul_hi_u32 s29, s46, s29
	s_add_i32 s46, s46, s29
	s_mul_hi_u32 s29, s1, s46
	s_mul_i32 s46, s29, s18
	s_sub_i32 s1, s1, s46
	s_add_i32 s47, s29, 1
	s_sub_i32 s46, s1, s18
	s_cmp_ge_u32 s1, s18
	s_cselect_b32 s29, s47, s29
	s_cselect_b32 s1, s46, s1
	s_add_i32 s46, s29, 1
	s_cmp_ge_u32 s1, s18
	s_cselect_b32 s1, s46, s29
	s_xor_b32 s1, s1, s19
	s_sub_i32 s1, s1, s19
	s_mul_i32 s17, s1, s17
	s_sub_i32 s2, s2, s17
	s_add_i32 s15, s15, s2
	s_mov_b64 s[18:19], -1

; #define PG8_STAGE(bufoff, gbase, voff) do { _Pragma("unroll") for (int _i = 0; _i < 2; ++_i) \
;         __builtin_amdgcn_global_load_lds((const unsigned*)((const char*)(gbase) + (voff)[_i]), (PG8_LAS unsigned*)(lds + (bufoff) + ldsw + _i * 8192), 16, 0, AUX_A); } while (0)
; #define PG8_STAGEB(bufoff, gbase, voff) do { _Pragma("unroll") for (int _i = 0; _i < 2; ++_i) \
;         __builtin_amdgcn_global_load_lds((const unsigned*)((const char*)(gbase) + (voff)[_i]), (PG8_LAS unsigned*)(lds + (bufoff) + ldsw + _i * 8192), 16, 0, AUX_B); } while (0)
; #define PG8_LDA(dst, b, h) do { _Pragma("unroll") for (int m = 0; m < 4; ++m) _Pragma("unroll") for (int k = 0; k < 2; ++k) dst[m][k] = *(const PG8_LAS bf16x8*)(lds + PG8_SA(b, h) + aoff + m * 2048 + k * 1024); } while (0)
; #define PG8_LDB(dst, b, h) do { _Pragma("unroll") for (int n = 0; n < 2; ++n) _Pragma("unroll") for (int k = 0; k < 2; ++k) dst[n][k] = *(const PG8_LAS bf16x8*)(lds + PG8_SB(b, h) + boff + n * 2048 + k * 1024); } while (0)
; #define PG8_MMA(ai, bj, At, Bt) do { __builtin_amdgcn_s_setprio(1); _Pragma("unroll") for (int m = 0; m < 4; ++m) _Pragma("unroll") for (int n = 0; n < 2; ++n) _Pragma("unroll") for (int k = 0; k < 2; ++k) \
;         acc[ai][bj][m][n] = __builtin_amdgcn_mfma_f32_16x16x32_bf16(Bt[n][k], At[m][k], acc[ai][bj][m][n], 0, 0, 0); __builtin_amdgcn_s_setprio(0); } while (0)
; #define PG8_WAIT_V(n) asm volatile("s_waitcnt vmcnt(" #n ")" ::: "memory")
; #define PG8_WAIT_L(n) asm volatile("s_waitcnt lgkmcnt(" #n ")" ::: "memory")
; #define PG8_BAR __builtin_amdgcn_s_barrier()
; #define PG8_SCHED __builtin_amdgcn_sched_barrier(0)
; template <class Epi, class Sched, bool ALIGN_EPI = false, bool SP2 = false>
; __device__ __forceinline__ void gemm_phase(PG8_LAS unsigned char* lds, const Gemm g, const Sched& S, const Epi& E) {
;     ...
;             PG8_LDB(B0, 0, 0); PG8_LDB(B1, 0, 1); PG8_SCHED; PG8_LDA(At, 0, 0); PG8_STAGE(PG8_SA(1, 1), a1 + hstep, voffA);
;             PG8_WAIT_V(8); PG8_WAIT_L(0); PG8_BAR; PG8_MMA(0, 0, At, B0); PG8_MMA(0, 1, At, B1); PG8_BAR; PG8_SCHED;
;             PG8_LDA(At, 0, 1); PG8_STAGEB(PG8_SB(0, 0), b2, voffB); PG8_STAGEB(PG8_SB(0, 1), b2 + hstep, voffB); PG8_STAGE(PG8_SA(0, 0), a2, voffA);
;             PG8_WAIT_V(8); PG8_WAIT_L(0); PG8_BAR; PG8_MMA(1, 0, At, B0); PG8_MMA(1, 1, At, B1); PG8_BAR; PG8_SCHED;
.Lrp_1067:
.Lpk_1067:
	s_add_i32 s81, s29, 2
	s_cmp_lt_u32 s29, 14
	s_cselect_b32 s0, 0, -16
	s_add_i32 s0, s81, s0
	s_ashr_i32 s1, s0, 31
	s_lshl_b64 s[0:1], s[0:1], 7
	s_add_u32 s2, s52, s0
	s_addc_u32 s46, s53, s1
	s_add_u32 s0, s42, s0
	s_addc_u32 s1, s43, s1
	s_cmp_eq_u32 s29, 14
	s_cselect_b32 s59, s15, s46
	s_cselect_b32 s58, s17, s2
	s_cselect_b32 s61, s92, s1
	s_cselect_b32 s60, s93, s0
	s_add_i32 s2, 0, 0x10000
	s_add_i32 s94, s2, s70
	s_add_i32 s46, 0, 0x14000
	s_add_i32 m0, s71, 0xc000
	s_add_i32 s84, s71, 0xe000
	s_add_i32 s95, s94, 0x2000
	s_add_u32 s62, s60, 0x40000
	s_addc_u32 s63, s61, 0
	s_add_i32 s96, s46, s70
	s_add_i32 s97, s96, 0x2000
	s_add_i32 vcc_lo, 0, 0x18000
	s_add_i32 vcc_hi, 0, 0x1c000
	s_add_u32 s56, s58, 0x40000
	s_addc_u32 s57, s59, 0
	s_add_i32 s1, vcc_lo, s70
	s_add_i32 s0, s1, 0x2000
	s_add_u32 s54, s60, 0x40080
	s_addc_u32 s55, s61, 0
	s_add_i32 s47, vcc_hi, s70
	s_add_i32 s46, s47, 0x2000
	s_cmp_gt_u32 s29, 13
	global_load_lds_dwordx4 v[146:147], off
	s_mov_b32 m0, s84
	s_nop 0
	global_load_lds_dwordx4 v[144:145], off
	s_waitcnt vmcnt(8)
	s_waitcnt lgkmcnt(0)
	s_setprio 1
	s_barrier
	v_mfma_f32_16x16x32_bf16 v[128:131], v[152:155], v[196:199], 0
	v_mfma_f32_16x16x32_bf16 v[128:131], v[156:159], v[200:203], v[128:131]
	v_mfma_f32_16x16x32_bf16 v[124:127], v[160:163], v[196:199], 0
	v_mfma_f32_16x16x32_bf16 v[124:127], v[164:167], v[200:203], v[124:127]
	v_mfma_f32_16x16x32_bf16 v[112:115], v[152:155], v[222:225], 0
	v_mfma_f32_16x16x32_bf16 v[112:115], v[156:159], v[226:229], v[112:115]
	v_mfma_f32_16x16x32_bf16 v[108:111], v[160:163], v[222:225], 0
	v_mfma_f32_16x16x32_bf16 v[108:111], v[164:167], v[226:229], v[108:111]
	v_mfma_f32_16x16x32_bf16 v[94:97], v[152:155], v[230:233], 0
	v_mfma_f32_16x16x32_bf16 v[94:97], v[156:159], v[234:237], v[94:97]
	v_mfma_f32_16x16x32_bf16 v[90:93], v[160:163], v[230:233], 0
	v_mfma_f32_16x16x32_bf16 v[90:93], v[164:167], v[234:237], v[90:93]
	v_mfma_f32_16x16x32_bf16 v[78:81], v[152:155], v[238:241], 0
	v_mfma_f32_16x16x32_bf16 v[78:81], v[156:159], v[242:245], v[78:81]
	v_mfma_f32_16x16x32_bf16 v[74:77], v[160:163], v[238:241], 0
	v_mfma_f32_16x16x32_bf16 v[74:77], v[164:167], v[242:245], v[74:77]
	s_setprio 0
	s_setprio 1
	v_mfma_f32_16x16x32_bf16 v[120:123], v[180:183], v[196:199], 0
	v_mfma_f32_16x16x32_bf16 v[120:123], v[184:187], v[200:203], v[120:123]
	v_mfma_f32_16x16x32_bf16 v[116:119], v[188:191], v[196:199], 0
	v_mfma_f32_16x16x32_bf16 v[116:119], v[192:195], v[200:203], v[116:119]
	v_mfma_f32_16x16x32_bf16 v[104:107], v[180:183], v[222:225], 0
	v_mfma_f32_16x16x32_bf16 v[104:107], v[184:187], v[226:229], v[104:107]
	v_mfma_f32_16x16x32_bf16 v[100:103], v[188:191], v[222:225], 0
	v_mfma_f32_16x16x32_bf16 v[100:103], v[192:195], v[226:229], v[100:103]
	v_mfma_f32_16x16x32_bf16 v[86:89], v[180:183], v[230:233], 0
	v_mfma_f32_16x16x32_bf16 v[86:89], v[184:187], v[234:237], v[86:89]
	v_mfma_f32_16x16x32_bf16 v[82:85], v[188:191], v[230:233], 0
	v_mfma_f32_16x16x32_bf16 v[82:85], v[192:195], v[234:237], v[82:85]
	v_mfma_f32_16x16x32_bf16 v[70:73], v[180:183], v[238:241], 0
	v_mfma_f32_16x16x32_bf16 v[70:73], v[184:187], v[242:245], v[70:73]
	s_setprio 2
	s_barrier
	v_mfma_f32_16x16x32_bf16 v[66:69], v[188:191], v[238:241], 0
	v_mfma_f32_16x16x32_bf16 v[66:69], v[192:195], v[242:245], v[66:69]
	s_setprio 0
	s_mov_b32 m0, s94
	v_lshl_add_u64 v[148:149], s[60:61], 0, v[136:137]
	ds_read_b128 v[196:199], v151 offset:16384
	ds_read_b128 v[200:203], v151 offset:17408
	ds_read_b128 v[222:225], v151 offset:18432
	ds_read_b128 v[226:229], v151 offset:19456
	ds_read_b128 v[230:233], v151 offset:20480
	ds_read_b128 v[234:237], v151 offset:21504
	ds_read_b128 v[238:241], v151 offset:22528
	ds_read_b128 v[242:245], v151 offset:23552
	global_load_lds_dwordx4 v[148:149], off
	v_lshl_add_u64 v[168:169], s[60:61], 0, v[132:133]
	s_mov_b32 m0, s95
	v_lshl_add_u64 v[172:173], s[62:63], 0, v[136:137]
	global_load_lds_dwordx4 v[168:169], off
	s_mov_b32 m0, s96
	v_lshl_add_u64 v[212:213], s[58:59], 0, v[134:135]
	global_load_lds_dwordx4 v[172:173], off
	v_lshl_add_u64 v[172:173], s[62:63], 0, v[132:133]
	s_mov_b32 m0, s97
	s_nop 0
	global_load_lds_dwordx4 v[172:173], off
	v_lshl_add_u64 v[172:173], s[58:59], 0, v[138:139]
	s_mov_b32 m0, s71
	s_nop 0
	global_load_lds_dwordx4 v[172:173], off
	s_mov_b32 m0, s75
	s_nop 0
	global_load_lds_dwordx4 v[212:213], off
	s_waitcnt vmcnt(8)
	s_waitcnt lgkmcnt(0)
	s_setprio 1
	s_barrier
	v_mfma_f32_16x16x32_bf16 v[62:65], v[152:155], v[196:199], 0
	v_mfma_f32_16x16x32_bf16 v[62:65], v[156:159], v[200:203], v[62:65]
	v_mfma_f32_16x16x32_bf16 v[58:61], v[160:163], v[196:199], 0
	v_mfma_f32_16x16x32_bf16 v[58:61], v[164:167], v[200:203], v[58:61]
	v_mfma_f32_16x16x32_bf16 v[46:49], v[152:155], v[222:225], 0
	v_mfma_f32_16x16x32_bf16 v[46:49], v[156:159], v[226:229], v[46:49]
	v_mfma_f32_16x16x32_bf16 v[42:45], v[160:163], v[222:225], 0
	v_mfma_f32_16x16x32_bf16 v[42:45], v[164:167], v[226:229], v[42:45]
	v_mfma_f32_16x16x32_bf16 v[30:33], v[152:155], v[230:233], 0
	v_mfma_f32_16x16x32_bf16 v[30:33], v[156:159], v[234:237], v[30:33]
	v_mfma_f32_16x16x32_bf16 v[26:29], v[160:163], v[230:233], 0
	v_mfma_f32_16x16x32_bf16 v[26:29], v[164:167], v[234:237], v[26:29]
	v_mfma_f32_16x16x32_bf16 v[14:17], v[152:155], v[238:241], 0
	v_mfma_f32_16x16x32_bf16 v[14:17], v[156:159], v[242:245], v[14:17]
	v_mfma_f32_16x16x32_bf16 v[10:13], v[160:163], v[238:241], 0
	v_mfma_f32_16x16x32_bf16 v[10:13], v[164:167], v[242:245], v[10:13]
	s_setprio 0
	s_setprio 1
	v_mfma_f32_16x16x32_bf16 v[54:57], v[180:183], v[196:199], 0
	v_mfma_f32_16x16x32_bf16 v[54:57], v[184:187], v[200:203], v[54:57]
	v_mfma_f32_16x16x32_bf16 v[50:53], v[188:191], v[196:199], 0
	v_mfma_f32_16x16x32_bf16 v[50:53], v[192:195], v[200:203], v[50:53]
	v_mfma_f32_16x16x32_bf16 v[38:41], v[180:183], v[222:225], 0
	v_mfma_f32_16x16x32_bf16 v[38:41], v[184:187], v[226:229], v[38:41]
	v_mfma_f32_16x16x32_bf16 v[34:37], v[188:191], v[222:225], 0
	v_mfma_f32_16x16x32_bf16 v[34:37], v[192:195], v[226:229], v[34:37]
	v_mfma_f32_16x16x32_bf16 v[22:25], v[180:183], v[230:233], 0
	v_mfma_f32_16x16x32_bf16 v[22:25], v[184:187], v[234:237], v[22:25]
	v_mfma_f32_16x16x32_bf16 v[18:21], v[188:191], v[230:233], 0
	v_mfma_f32_16x16x32_bf16 v[18:21], v[192:195], v[234:237], v[18:21]
	v_mfma_f32_16x16x32_bf16 v[6:9], v[180:183], v[238:241], 0
	v_mfma_f32_16x16x32_bf16 v[6:9], v[184:187], v[242:245], v[6:9]
	s_setprio 2
	s_barrier
; #define PG8_STAGE(bufoff, gbase, voff) do { _Pragma("unroll") for (int _i = 0; _i < 2; ++_i) \
;         __builtin_amdgcn_global_load_lds((const unsigned*)((const char*)(gbase) + (voff)[_i]), (PG8_LAS unsigned*)(lds + (bufoff) + ldsw + _i * 8192), 16, 0, AUX_A); } while (0)
; #define PG8_STAGEB(bufoff, gbase, voff) do { _Pragma("unroll") for (int _i = 0; _i < 2; ++_i) \
;         __builtin_amdgcn_global_load_lds((const unsigned*)((const char*)(gbase) + (voff)[_i]), (PG8_LAS unsigned*)(lds + (bufoff) + ldsw + _i * 8192), 16, 0, AUX_B); } while (0)
; #define PG8_LDA(dst, b, h) do { _Pragma("unroll") for (int m = 0; m < 4; ++m) _Pragma("unroll") for (int k = 0; k < 2; ++k) dst[m][k] = *(const PG8_LAS bf16x8*)(lds + PG8_SA(b, h) + aoff + m * 2048 + k * 1024); } while (0)
; #define PG8_LDB(dst, b, h) do { _Pragma("unroll") for (int n = 0; n < 2; ++n) _Pragma("unroll") for (int k = 0; k < 2; ++k) dst[n][k] = *(const PG8_LAS bf16x8*)(lds + PG8_SB(b, h) + boff + n * 2048 + k * 1024); } while (0)
; #define PG8_MMA(ai, bj, At, Bt) do { __builtin_amdgcn_s_setprio(1); _Pragma("unroll") for (int m = 0; m < 4; ++m) _Pragma("unroll") for (int n = 0; n < 2; ++n) _Pragma("unroll") for (int k = 0; k < 2; ++k) \
;         acc[ai][bj][m][n] = __builtin_amdgcn_mfma_f32_16x16x32_bf16(Bt[n][k], At[m][k], acc[ai][bj][m][n], 0, 0, 0); __builtin_amdgcn_s_setprio(0); } while (0)
; #define PG8_WAIT_V(n) asm volatile("s_waitcnt vmcnt(" #n ")" ::: "memory")
; #define PG8_WAIT_L(n) asm volatile("s_waitcnt lgkmcnt(" #n ")" ::: "memory")
; #define PG8_BAR __builtin_amdgcn_s_barrier()
; #define PG8_SCHED __builtin_amdgcn_sched_barrier(0)
; template <class Epi, class Sched, bool ALIGN_EPI = false, bool SP2 = false>
; __device__ __forceinline__ void gemm_phase(PG8_LAS unsigned char* lds, const Gemm g, const Sched& S, const Epi& E) {
;     ...
;             PG8_LDB(B0, 1, 0); PG8_LDB(B1, 1, 1); PG8_SCHED; PG8_LDA(At, 1, 0); PG8_STAGE(PG8_SA(0, 1), a2 + hstep, voffA);
;             PG8_WAIT_V(8); PG8_WAIT_L(0); PG8_BAR; PG8_MMA(0, 0, At, B0); PG8_MMA(0, 1, At, B1); PG8_BAR; PG8_SCHED;
;             PG8_LDA(At, 1, 1); PG8_STAGEB(PG8_SB(1, 0), b3, voffB); PG8_STAGEB(PG8_SB(1, 1), b3 + hstep, voffB); PG8_STAGE(PG8_SA(1, 0), a3, voffA);
;             PG8_WAIT_V(8); PG8_WAIT_L(0); PG8_BAR; PG8_MMA(1, 0, At, B0); PG8_MMA(1, 1, At, B1); PG8_BAR; PG8_SCHED;
	v_mfma_f32_16x16x32_bf16 v[2:5], v[188:191], v[238:241], 0
	v_mfma_f32_16x16x32_bf16 v[2:5], v[192:195], v[242:245], v[2:5]
	s_setprio 0
	v_add_u32_e32 v164, vcc_lo, v99
	v_add_u32_e32 v192, vcc_hi, v99
	ds_read_b128 v[152:155], v164
	ds_read_b128 v[156:159], v164 offset:1024
	ds_read_b128 v[160:163], v164 offset:2048
	ds_read_b128 v[164:167], v164 offset:3072
	ds_read_b128 v[180:183], v192
	ds_read_b128 v[184:187], v192 offset:1024
	ds_read_b128 v[188:191], v192 offset:2048
	ds_read_b128 v[192:195], v192 offset:3072
	s_mov_b32 m0, s78
	v_lshl_add_u64 v[246:247], s[56:57], 0, v[138:139]
	ds_read_b128 v[196:199], v151 offset:32768
	ds_read_b128 v[200:203], v151 offset:33792
	ds_read_b128 v[222:225], v151 offset:34816
	ds_read_b128 v[226:229], v151 offset:35840
	ds_read_b128 v[230:233], v151 offset:36864
	ds_read_b128 v[234:237], v151 offset:37888
	ds_read_b128 v[238:241], v151 offset:38912
	ds_read_b128 v[242:245], v151 offset:39936
	global_load_lds_dwordx4 v[246:247], off
	v_lshl_add_u64 v[246:247], s[56:57], 0, v[134:135]
	s_mov_b32 m0, s82
	s_nop 0
	global_load_lds_dwordx4 v[246:247], off
	s_waitcnt vmcnt(8)
	s_waitcnt lgkmcnt(0)
	s_setprio 1
	s_barrier
	v_mfma_f32_16x16x32_bf16 v[128:131], v[152:155], v[196:199], v[128:131]
	v_mfma_f32_16x16x32_bf16 v[128:131], v[156:159], v[200:203], v[128:131]
	v_mfma_f32_16x16x32_bf16 v[124:127], v[160:163], v[196:199], v[124:127]
	v_mfma_f32_16x16x32_bf16 v[124:127], v[164:167], v[200:203], v[124:127]
	v_mfma_f32_16x16x32_bf16 v[112:115], v[152:155], v[222:225], v[112:115]
	v_mfma_f32_16x16x32_bf16 v[112:115], v[156:159], v[226:229], v[112:115]
	v_mfma_f32_16x16x32_bf16 v[108:111], v[160:163], v[222:225], v[108:111]
	v_mfma_f32_16x16x32_bf16 v[108:111], v[164:167], v[226:229], v[108:111]
	v_mfma_f32_16x16x32_bf16 v[94:97], v[152:155], v[230:233], v[94:97]
	v_mfma_f32_16x16x32_bf16 v[94:97], v[156:159], v[234:237], v[94:97]
	v_mfma_f32_16x16x32_bf16 v[90:93], v[160:163], v[230:233], v[90:93]
	v_mfma_f32_16x16x32_bf16 v[90:93], v[164:167], v[234:237], v[90:93]
	v_mfma_f32_16x16x32_bf16 v[78:81], v[152:155], v[238:241], v[78:81]
	v_mfma_f32_16x16x32_bf16 v[78:81], v[156:159], v[242:245], v[78:81]
	v_mfma_f32_16x16x32_bf16 v[74:77], v[160:163], v[238:241], v[74:77]
	v_mfma_f32_16x16x32_bf16 v[74:77], v[164:167], v[242:245], v[74:77]
	s_setprio 0
	s_setprio 1
	v_mfma_f32_16x16x32_bf16 v[120:123], v[180:183], v[196:199], v[120:123]
	v_mfma_f32_16x16x32_bf16 v[120:123], v[184:187], v[200:203], v[120:123]
	v_mfma_f32_16x16x32_bf16 v[116:119], v[188:191], v[196:199], v[116:119]
	v_mfma_f32_16x16x32_bf16 v[116:119], v[192:195], v[200:203], v[116:119]
	v_mfma_f32_16x16x32_bf16 v[104:107], v[180:183], v[222:225], v[104:107]
	v_mfma_f32_16x16x32_bf16 v[104:107], v[184:187], v[226:229], v[104:107]
	v_mfma_f32_16x16x32_bf16 v[100:103], v[188:191], v[222:225], v[100:103]
	v_mfma_f32_16x16x32_bf16 v[100:103], v[192:195], v[226:229], v[100:103]
	v_mfma_f32_16x16x32_bf16 v[86:89], v[180:183], v[230:233], v[86:89]
	v_mfma_f32_16x16x32_bf16 v[86:89], v[184:187], v[234:237], v[86:89]
	v_mfma_f32_16x16x32_bf16 v[82:85], v[188:191], v[230:233], v[82:85]
	v_mfma_f32_16x16x32_bf16 v[82:85], v[192:195], v[234:237], v[82:85]
	v_mfma_f32_16x16x32_bf16 v[70:73], v[180:183], v[238:241], v[70:73]
	v_mfma_f32_16x16x32_bf16 v[70:73], v[184:187], v[242:245], v[70:73]
	s_setprio 2
	s_barrier
	v_mfma_f32_16x16x32_bf16 v[66:69], v[188:191], v[238:241], v[66:69]
	v_mfma_f32_16x16x32_bf16 v[66:69], v[192:195], v[242:245], v[66:69]
	s_setprio 0
	s_mov_b32 m0, s1
	v_lshl_add_u64 v[148:149], v[148:149], 0, s[76:77]
	ds_read_b128 v[196:199], v151 offset:49152
	ds_read_b128 v[200:203], v151 offset:50176
	ds_read_b128 v[222:225], v151 offset:51200
	ds_read_b128 v[226:229], v151 offset:52224
	ds_read_b128 v[230:233], v151 offset:53248
	ds_read_b128 v[234:237], v151 offset:54272
	ds_read_b128 v[238:241], v151 offset:55296
	ds_read_b128 v[242:245], v151 offset:56320
	global_load_lds_dwordx4 v[148:149], off
	v_lshl_add_u64 v[148:149], v[168:169], 0, s[76:77]
	s_mov_b32 m0, s0
	s_nop 0
	global_load_lds_dwordx4 v[148:149], off
	v_lshl_add_u64 v[148:149], s[54:55], 0, v[136:137]
	s_mov_b32 m0, s47
	s_nop 0
	global_load_lds_dwordx4 v[148:149], off
	v_lshl_add_u64 v[148:149], s[54:55], 0, v[132:133]
	s_mov_b32 m0, s46
	s_nop 0
	global_load_lds_dwordx4 v[148:149], off
	v_lshl_add_u64 v[148:149], v[172:173], 0, s[76:77]
	s_mov_b32 m0, s83
	s_nop 0
	global_load_lds_dwordx4 v[148:149], off
	v_lshl_add_u64 v[148:149], v[212:213], 0, s[76:77]
	s_mov_b32 m0, s88
	s_nop 0
	global_load_lds_dwordx4 v[148:149], off
	s_waitcnt vmcnt(8)
	s_waitcnt lgkmcnt(0)
	s_setprio 1
	s_barrier
	v_mfma_f32_16x16x32_bf16 v[62:65], v[152:155], v[196:199], v[62:65]
	v_mfma_f32_16x16x32_bf16 v[62:65], v[156:159], v[200:203], v[62:65]
	v_mfma_f32_16x16x32_bf16 v[58:61], v[160:163], v[196:199], v[58:61]
	v_mfma_f32_16x16x32_bf16 v[58:61], v[164:167], v[200:203], v[58:61]
	v_mfma_f32_16x16x32_bf16 v[46:49], v[152:155], v[222:225], v[46:49]
	v_mfma_f32_16x16x32_bf16 v[46:49], v[156:159], v[226:229], v[46:49]
	v_mfma_f32_16x16x32_bf16 v[42:45], v[160:163], v[222:225], v[42:45]
	v_mfma_f32_16x16x32_bf16 v[42:45], v[164:167], v[226:229], v[42:45]
	v_mfma_f32_16x16x32_bf16 v[30:33], v[152:155], v[230:233], v[30:33]
	v_mfma_f32_16x16x32_bf16 v[30:33], v[156:159], v[234:237], v[30:33]
	v_mfma_f32_16x16x32_bf16 v[26:29], v[160:163], v[230:233], v[26:29]
	v_mfma_f32_16x16x32_bf16 v[26:29], v[164:167], v[234:237], v[26:29]
	v_mfma_f32_16x16x32_bf16 v[14:17], v[152:155], v[238:241], v[14:17]
	v_mfma_f32_16x16x32_bf16 v[14:17], v[156:159], v[242:245], v[14:17]
	v_mfma_f32_16x16x32_bf16 v[10:13], v[160:163], v[238:241], v[10:13]
	v_mfma_f32_16x16x32_bf16 v[10:13], v[164:167], v[242:245], v[10:13]
	s_setprio 0
	s_setprio 1
	v_mfma_f32_16x16x32_bf16 v[54:57], v[180:183], v[196:199], v[54:57]
	v_mfma_f32_16x16x32_bf16 v[54:57], v[184:187], v[200:203], v[54:57]
	v_mfma_f32_16x16x32_bf16 v[50:53], v[188:191], v[196:199], v[50:53]
	v_mfma_f32_16x16x32_bf16 v[50:53], v[192:195], v[200:203], v[50:53]
	v_mfma_f32_16x16x32_bf16 v[38:41], v[180:183], v[222:225], v[38:41]
	v_mfma_f32_16x16x32_bf16 v[38:41], v[184:187], v[226:229], v[38:41]
	v_mfma_f32_16x16x32_bf16 v[34:37], v[188:191], v[222:225], v[34:37]
	v_mfma_f32_16x16x32_bf16 v[34:37], v[192:195], v[226:229], v[34:37]
	v_mfma_f32_16x16x32_bf16 v[22:25], v[180:183], v[230:233], v[22:25]
	v_mfma_f32_16x16x32_bf16 v[22:25], v[184:187], v[234:237], v[22:25]
	v_mfma_f32_16x16x32_bf16 v[18:21], v[188:191], v[230:233], v[18:21]
	v_mfma_f32_16x16x32_bf16 v[18:21], v[192:195], v[234:237], v[18:21]
	v_mfma_f32_16x16x32_bf16 v[6:9], v[180:183], v[238:241], v[6:9]
	v_mfma_f32_16x16x32_bf16 v[6:9], v[184:187], v[242:245], v[6:9]
	s_setprio 2
	s_barrier
	v_mfma_f32_16x16x32_bf16 v[2:5], v[188:191], v[238:241], v[2:5]
	v_mfma_f32_16x16x32_bf16 v[2:5], v[192:195], v[242:245], v[2:5]
	s_setprio 0
	v_lshl_add_u64 v[144:145], v[144:145], 0, s[86:87]
	v_lshl_add_u64 v[146:147], v[146:147], 0, s[86:87]
	s_mov_b32 s29, s81
	s_cbranch_scc1 .Lpx_1067

; #define PG8_STAGE(bufoff, gbase, voff) do { _Pragma("unroll") for (int _i = 0; _i < 2; ++_i) \
;         __builtin_amdgcn_global_load_lds((const unsigned*)((const char*)(gbase) + (voff)[_i]), (PG8_LAS unsigned*)(lds + (bufoff) + ldsw + _i * 8192), 16, 0, AUX_A); } while (0)
; #define PG8_LDA(dst, b, h) do { _Pragma("unroll") for (int m = 0; m < 4; ++m) _Pragma("unroll") for (int k = 0; k < 2; ++k) dst[m][k] = *(const PG8_LAS bf16x8*)(lds + PG8_SA(b, h) + aoff + m * 2048 + k * 1024); } while (0)
; #define PG8_LDB(dst, b, h) do { _Pragma("unroll") for (int n = 0; n < 2; ++n) _Pragma("unroll") for (int k = 0; k < 2; ++k) dst[n][k] = *(const PG8_LAS bf16x8*)(lds + PG8_SB(b, h) + boff + n * 2048 + k * 1024); } while (0)
; #define PG8_SCHED __builtin_amdgcn_sched_barrier(0)
;     __host__ __device__ bool next(int i, Unit& u) const {
;         const long L = (long)i * G + c; if (L >= nwg) return false;
;         int wgid = (int)L; { const int q = nwg / NXCD, r = nwg % NXCD, xcd = wgid % NXCD, off = wgid / NXCD; wgid = (xcd < r ? xcd * (q + 1) : r * (q + 1) + (xcd - r) * q) + off; }
;         if (ORD_TR > 0) {
;             const int nig = ORD_TR * nM, gid = wgid / nig, fn = gid * ORD_TR, gsz = (nN - fn) < ORD_TR ? (nN - fn) : ORD_TR;
;             u.pn = fn + ((wgid % nig) % gsz); u.pm = (wgid % nig) / gsz; u.kt0 = 0; u.nkt = nkt; u.slab = -1; u.krot = 0; return true; }
;         const int nig = WGM * nN, gid = wgid / nig, fm = gid * WGM, gsz = (nM - fm) < WGM ? (nM - fm) : WGM;
;         u.pm = fm + ((wgid % nig) % gsz); u.pn = (wgid % nig) / gsz; u.kt0 = 0; u.nkt = nkt; u.slab = -1; u.krot = KROT ? 2 * (((c & 7) * (nkt >> 1)) >> 3) : 0; return true;
; template <class Epi, class Sched, bool ALIGN_EPI = false, bool SP2 = false>
; __device__ __forceinline__ void gemm_phase(PG8_LAS unsigned char* lds, const Gemm g, const Sched& S, const Epi& E) {
;     ...
;             PG8_LDB(B0, 0, 0); PG8_LDB(B1, 0, 1); PG8_SCHED; PG8_LDA(At, 0, 0); PG8_STAGE(PG8_SA(1, 1), a1 + hstep, voffA);
.LBB0_1149:
	v_add_u32_e32 v162, 0x10000, v99
	v_add_u32_e32 v166, 0x14000, v99
	ds_read_b128 v[148:151], v162
	ds_read_b128 v[154:157], v162 offset:1024
	ds_read_b128 v[158:161], v162 offset:2048
	ds_read_b128 v[162:165], v162 offset:3072
	ds_read_b128 v[180:183], v166
	ds_read_b128 v[184:187], v166 offset:1024
	ds_read_b128 v[188:191], v166 offset:2048
	ds_read_b128 v[192:195], v166 offset:3072
	ds_read_b128 v[196:199], v153
	ds_read_b128 v[200:203], v153 offset:1024
	ds_read_b128 v[222:225], v153 offset:2048
	ds_read_b128 v[226:229], v153 offset:3072
	ds_read_b128 v[230:233], v153 offset:4096
	ds_read_b128 v[234:237], v153 offset:5120
	ds_read_b128 v[238:241], v153 offset:6144
	ds_read_b128 v[242:245], v153 offset:7168
	s_add_i32 s89, s0, 1
	s_and_b64 vcc, exec, s[36:37]
	s_mov_b64 s[40:41], -1
	s_cbranch_vccnz .LBB0_1152
	v_readlane_b32 s1, v251, 56
	s_mul_i32 s1, s89, s1
	s_mul_hi_u32 s2, s89, s68
	s_add_i32 s2, s2, s1
	s_mul_i32 s1, s89, s68
	s_add_u32 s48, s1, s92
	v_readlane_b32 s1, v251, 55
	s_addc_u32 s49, s2, s1
	v_cmp_gt_i64_e32 vcc, s[48:49], v[174:175]
	s_mov_b64 s[40:41], 0
	s_mov_b64 s[42:43], 0
	s_mov_b32 s19, s18
	s_mov_b32 s1, s38
	s_cbranch_vccnz .LBB0_1152
	s_ashr_i32 s1, s48, 31
	s_lshr_b32 s1, s1, 29
	s_add_i32 s1, s48, s1
	s_ashr_i32 s2, s1, 3
	s_and_b32 s1, s1, -8
	s_sub_i32 s1, s48, s1
	s_cmp_lt_i32 s1, 0
	s_cselect_b32 s19, 37, 36
	s_mul_i32 s1, s1, s19
	s_add_i32 s1, s1, s2
	s_mul_hi_i32 s2, s1, 0x2aaaaaab
	s_lshr_b32 s19, s2, 31
	s_ashr_i32 s2, s2, 3
	s_add_i32 s2, s2, s19
	s_mul_i32 s19, s2, 6
	s_sub_i32 s29, 36, s19
	s_min_i32 s29, s29, 6
	s_abs_i32 s39, s29
	v_cvt_f32_u32_e32 v2, s39
	s_sub_i32 s43, 0, s39
	s_mul_i32 s2, s2, 48
	s_sub_i32 s2, s1, s2
	v_rcp_iflag_f32_e32 v2, v2
	s_abs_i32 s1, s2
	s_xor_b32 s42, s2, s29
	s_ashr_i32 s42, s42, 31
	v_mul_f32_e32 v2, 0x4f7ffffe, v2
	v_cvt_u32_f32_e32 v2, v2
	s_nop 0
	v_readfirstlane_b32 s46, v2
	s_mul_i32 s43, s43, s46
	s_mul_hi_u32 s43, s46, s43
	s_add_i32 s46, s46, s43
	s_mul_hi_u32 s43, s1, s46
	s_mul_i32 s46, s43, s39
	s_sub_i32 s1, s1, s46
	s_add_i32 s47, s43, 1
	s_sub_i32 s46, s1, s39
	s_cmp_ge_u32 s1, s39
	s_cselect_b32 s43, s47, s43
	s_cselect_b32 s1, s46, s1
	s_add_i32 s46, s43, 1
	s_cmp_ge_u32 s1, s39
	s_cselect_b32 s1, s46, s43
	s_xor_b32 s1, s1, s42
	s_sub_i32 s1, s1, s42
	s_mul_i32 s29, s1, s29
	s_sub_i32 s2, s2, s29
	s_add_i32 s19, s19, s2
	s_mov_b64 s[42:43], -1

; #define PG8_STAGE(bufoff, gbase, voff) do { _Pragma("unroll") for (int _i = 0; _i < 2; ++_i) \
;         __builtin_amdgcn_global_load_lds((const unsigned*)((const char*)(gbase) + (voff)[_i]), (PG8_LAS unsigned*)(lds + (bufoff) + ldsw + _i * 8192), 16, 0, AUX_A); } while (0)
; #define PG8_STAGEB(bufoff, gbase, voff) do { _Pragma("unroll") for (int _i = 0; _i < 2; ++_i) \
;         __builtin_amdgcn_global_load_lds((const unsigned*)((const char*)(gbase) + (voff)[_i]), (PG8_LAS unsigned*)(lds + (bufoff) + ldsw + _i * 8192), 16, 0, AUX_B); } while (0)
; #define PG8_LDA(dst, b, h) do { _Pragma("unroll") for (int m = 0; m < 4; ++m) _Pragma("unroll") for (int k = 0; k < 2; ++k) dst[m][k] = *(const PG8_LAS bf16x8*)(lds + PG8_SA(b, h) + aoff + m * 2048 + k * 1024); } while (0)
; #define PG8_LDB(dst, b, h) do { _Pragma("unroll") for (int n = 0; n < 2; ++n) _Pragma("unroll") for (int k = 0; k < 2; ++k) dst[n][k] = *(const PG8_LAS bf16x8*)(lds + PG8_SB(b, h) + boff + n * 2048 + k * 1024); } while (0)
; #define PG8_MMA(ai, bj, At, Bt) do { __builtin_amdgcn_s_setprio(1); _Pragma("unroll") for (int m = 0; m < 4; ++m) _Pragma("unroll") for (int n = 0; n < 2; ++n) _Pragma("unroll") for (int k = 0; k < 2; ++k) \
;         acc[ai][bj][m][n] = __builtin_amdgcn_mfma_f32_16x16x32_bf16(Bt[n][k], At[m][k], acc[ai][bj][m][n], 0, 0, 0); __builtin_amdgcn_s_setprio(0); } while (0)
; #define PG8_WAIT_V(n) asm volatile("s_waitcnt vmcnt(" #n ")" ::: "memory")
; #define PG8_WAIT_L(n) asm volatile("s_waitcnt lgkmcnt(" #n ")" ::: "memory")
; #define PG8_BAR __builtin_amdgcn_s_barrier()
; #define PG8_SCHED __builtin_amdgcn_sched_barrier(0)
; template <class Epi, class Sched, bool ALIGN_EPI = false, bool SP2 = false>
; __device__ __forceinline__ void gemm_phase(PG8_LAS unsigned char* lds, const Gemm g, const Sched& S, const Epi& E) {
;     ...
;             PG8_LDB(B0, 0, 0); PG8_LDB(B1, 0, 1); PG8_SCHED; PG8_LDA(At, 0, 0); PG8_STAGE(PG8_SA(1, 1), a1 + hstep, voffA);
;             PG8_WAIT_V(8); PG8_WAIT_L(0); PG8_BAR; PG8_MMA(0, 0, At, B0); PG8_MMA(0, 1, At, B1); PG8_BAR; PG8_SCHED;
;             PG8_LDA(At, 0, 1); PG8_STAGEB(PG8_SB(0, 0), b2, voffB); PG8_STAGEB(PG8_SB(0, 1), b2 + hstep, voffB); PG8_STAGE(PG8_SA(0, 0), a2, voffA);
;             PG8_WAIT_V(8); PG8_WAIT_L(0); PG8_BAR; PG8_MMA(1, 0, At, B0); PG8_MMA(1, 1, At, B1); PG8_BAR; PG8_SCHED;
.Lrp_1157:
.Lpk_1157:
	s_add_i32 s81, s29, 2
	s_cmp_lt_u32 s29, 14
	s_cselect_b32 s0, 0, -16
	s_add_i32 s0, s81, s0
	s_ashr_i32 s1, s0, 31
	s_lshl_b64 s[0:1], s[0:1], 7
	s_add_u32 s2, s52, s0
	s_addc_u32 s46, s53, s1
	s_add_u32 s0, s50, s0
	s_addc_u32 s1, s51, s1
	s_cmp_eq_u32 s29, 14
	s_cselect_b32 s59, s19, s46
	s_cselect_b32 s58, s39, s2
	s_cselect_b32 s61, s92, s1
	s_cselect_b32 s60, s93, s0
	s_add_i32 s2, 0, 0x10000
	s_add_i32 s94, s2, s70
	s_add_i32 s46, 0, 0x14000
	s_add_i32 m0, s71, 0xc000
	s_add_i32 s84, s71, 0xe000
	s_add_i32 s95, s94, 0x2000
	s_add_u32 s62, s60, 0x40000
	s_addc_u32 s63, s61, 0
	s_add_i32 s96, s46, s70
	s_add_i32 s97, s96, 0x2000
	s_add_i32 vcc_lo, 0, 0x18000
	s_add_i32 vcc_hi, 0, 0x1c000
	s_add_u32 s56, s58, 0x40000
	s_addc_u32 s57, s59, 0
	s_add_i32 s1, vcc_lo, s70
	s_add_i32 s0, s1, 0x2000
	s_add_u32 s54, s60, 0x40080
	s_addc_u32 s55, s61, 0
	s_add_i32 s47, vcc_hi, s70
	s_add_i32 s46, s47, 0x2000
	s_cmp_gt_u32 s29, 13
	global_load_lds_dwordx4 v[146:147], off
	s_mov_b32 m0, s84
	s_nop 0
	global_load_lds_dwordx4 v[144:145], off
	s_waitcnt vmcnt(8)
	s_waitcnt lgkmcnt(0)
	s_setprio 1
	s_barrier
	v_mfma_f32_16x16x32_bf16 v[128:131], v[148:151], v[196:199], 0
	v_mfma_f32_16x16x32_bf16 v[128:131], v[154:157], v[200:203], v[128:131]
	v_mfma_f32_16x16x32_bf16 v[124:127], v[158:161], v[196:199], 0
	v_mfma_f32_16x16x32_bf16 v[124:127], v[162:165], v[200:203], v[124:127]
	v_mfma_f32_16x16x32_bf16 v[112:115], v[148:151], v[222:225], 0
	v_mfma_f32_16x16x32_bf16 v[112:115], v[154:157], v[226:229], v[112:115]
	v_mfma_f32_16x16x32_bf16 v[108:111], v[158:161], v[222:225], 0
	v_mfma_f32_16x16x32_bf16 v[108:111], v[162:165], v[226:229], v[108:111]
	v_mfma_f32_16x16x32_bf16 v[94:97], v[148:151], v[230:233], 0
	v_mfma_f32_16x16x32_bf16 v[94:97], v[154:157], v[234:237], v[94:97]
	v_mfma_f32_16x16x32_bf16 v[90:93], v[158:161], v[230:233], 0
	v_mfma_f32_16x16x32_bf16 v[90:93], v[162:165], v[234:237], v[90:93]
	v_mfma_f32_16x16x32_bf16 v[78:81], v[148:151], v[238:241], 0
	v_mfma_f32_16x16x32_bf16 v[78:81], v[154:157], v[242:245], v[78:81]
	v_mfma_f32_16x16x32_bf16 v[74:77], v[158:161], v[238:241], 0
	v_mfma_f32_16x16x32_bf16 v[74:77], v[162:165], v[242:245], v[74:77]
	s_setprio 0
	s_setprio 1
	v_mfma_f32_16x16x32_bf16 v[120:123], v[180:183], v[196:199], 0
	v_mfma_f32_16x16x32_bf16 v[120:123], v[184:187], v[200:203], v[120:123]
	v_mfma_f32_16x16x32_bf16 v[116:119], v[188:191], v[196:199], 0
	v_mfma_f32_16x16x32_bf16 v[116:119], v[192:195], v[200:203], v[116:119]
	v_mfma_f32_16x16x32_bf16 v[104:107], v[180:183], v[222:225], 0
	v_mfma_f32_16x16x32_bf16 v[104:107], v[184:187], v[226:229], v[104:107]
	v_mfma_f32_16x16x32_bf16 v[100:103], v[188:191], v[222:225], 0
	v_mfma_f32_16x16x32_bf16 v[100:103], v[192:195], v[226:229], v[100:103]
	v_mfma_f32_16x16x32_bf16 v[86:89], v[180:183], v[230:233], 0
	v_mfma_f32_16x16x32_bf16 v[86:89], v[184:187], v[234:237], v[86:89]
	v_mfma_f32_16x16x32_bf16 v[82:85], v[188:191], v[230:233], 0
	v_mfma_f32_16x16x32_bf16 v[82:85], v[192:195], v[234:237], v[82:85]
	v_mfma_f32_16x16x32_bf16 v[70:73], v[180:183], v[238:241], 0
	v_mfma_f32_16x16x32_bf16 v[70:73], v[184:187], v[242:245], v[70:73]
	s_setprio 2
	s_barrier
	v_mfma_f32_16x16x32_bf16 v[66:69], v[188:191], v[238:241], 0
	v_mfma_f32_16x16x32_bf16 v[66:69], v[192:195], v[242:245], v[66:69]
	s_setprio 0
	s_mov_b32 m0, s94
	v_lshl_add_u64 v[166:167], s[60:61], 0, v[136:137]
	ds_read_b128 v[196:199], v153 offset:16384
	ds_read_b128 v[200:203], v153 offset:17408
	ds_read_b128 v[222:225], v153 offset:18432
	ds_read_b128 v[226:229], v153 offset:19456
	ds_read_b128 v[230:233], v153 offset:20480
	ds_read_b128 v[234:237], v153 offset:21504
	ds_read_b128 v[238:241], v153 offset:22528
	ds_read_b128 v[242:245], v153 offset:23552
	global_load_lds_dwordx4 v[166:167], off
	v_lshl_add_u64 v[168:169], s[60:61], 0, v[132:133]
	s_mov_b32 m0, s95
	v_lshl_add_u64 v[172:173], s[62:63], 0, v[136:137]
	global_load_lds_dwordx4 v[168:169], off
	s_mov_b32 m0, s96
	v_lshl_add_u64 v[212:213], s[58:59], 0, v[134:135]
	global_load_lds_dwordx4 v[172:173], off
	v_lshl_add_u64 v[172:173], s[62:63], 0, v[132:133]
	s_mov_b32 m0, s97
	s_nop 0
	global_load_lds_dwordx4 v[172:173], off
	v_lshl_add_u64 v[172:173], s[58:59], 0, v[138:139]
	s_mov_b32 m0, s71
	s_nop 0
	global_load_lds_dwordx4 v[172:173], off
	s_mov_b32 m0, s75
	s_nop 0
	global_load_lds_dwordx4 v[212:213], off
	s_waitcnt vmcnt(8)
	s_waitcnt lgkmcnt(0)
	s_setprio 1
	s_barrier
	v_mfma_f32_16x16x32_bf16 v[62:65], v[148:151], v[196:199], 0
	v_mfma_f32_16x16x32_bf16 v[62:65], v[154:157], v[200:203], v[62:65]
	v_mfma_f32_16x16x32_bf16 v[58:61], v[158:161], v[196:199], 0
	v_mfma_f32_16x16x32_bf16 v[58:61], v[162:165], v[200:203], v[58:61]
	v_mfma_f32_16x16x32_bf16 v[46:49], v[148:151], v[222:225], 0
	v_mfma_f32_16x16x32_bf16 v[46:49], v[154:157], v[226:229], v[46:49]
	v_mfma_f32_16x16x32_bf16 v[42:45], v[158:161], v[222:225], 0
	v_mfma_f32_16x16x32_bf16 v[42:45], v[162:165], v[226:229], v[42:45]
	v_mfma_f32_16x16x32_bf16 v[30:33], v[148:151], v[230:233], 0
	v_mfma_f32_16x16x32_bf16 v[30:33], v[154:157], v[234:237], v[30:33]
	v_mfma_f32_16x16x32_bf16 v[26:29], v[158:161], v[230:233], 0
	v_mfma_f32_16x16x32_bf16 v[26:29], v[162:165], v[234:237], v[26:29]
	v_mfma_f32_16x16x32_bf16 v[14:17], v[148:151], v[238:241], 0
	v_mfma_f32_16x16x32_bf16 v[14:17], v[154:157], v[242:245], v[14:17]
	v_mfma_f32_16x16x32_bf16 v[10:13], v[158:161], v[238:241], 0
	v_mfma_f32_16x16x32_bf16 v[10:13], v[162:165], v[242:245], v[10:13]
	s_setprio 0
	s_setprio 1
	v_mfma_f32_16x16x32_bf16 v[54:57], v[180:183], v[196:199], 0
	v_mfma_f32_16x16x32_bf16 v[54:57], v[184:187], v[200:203], v[54:57]
	v_mfma_f32_16x16x32_bf16 v[50:53], v[188:191], v[196:199], 0
	v_mfma_f32_16x16x32_bf16 v[50:53], v[192:195], v[200:203], v[50:53]
	v_mfma_f32_16x16x32_bf16 v[38:41], v[180:183], v[222:225], 0
	v_mfma_f32_16x16x32_bf16 v[38:41], v[184:187], v[226:229], v[38:41]
	v_mfma_f32_16x16x32_bf16 v[34:37], v[188:191], v[222:225], 0
	v_mfma_f32_16x16x32_bf16 v[34:37], v[192:195], v[226:229], v[34:37]
	v_mfma_f32_16x16x32_bf16 v[22:25], v[180:183], v[230:233], 0
	v_mfma_f32_16x16x32_bf16 v[22:25], v[184:187], v[234:237], v[22:25]
	v_mfma_f32_16x16x32_bf16 v[18:21], v[188:191], v[230:233], 0
	v_mfma_f32_16x16x32_bf16 v[18:21], v[192:195], v[234:237], v[18:21]
	v_mfma_f32_16x16x32_bf16 v[6:9], v[180:183], v[238:241], 0
	v_mfma_f32_16x16x32_bf16 v[6:9], v[184:187], v[242:245], v[6:9]
	s_setprio 2
	s_barrier
; #define PG8_STAGE(bufoff, gbase, voff) do { _Pragma("unroll") for (int _i = 0; _i < 2; ++_i) \
;         __builtin_amdgcn_global_load_lds((const unsigned*)((const char*)(gbase) + (voff)[_i]), (PG8_LAS unsigned*)(lds + (bufoff) + ldsw + _i * 8192), 16, 0, AUX_A); } while (0)
; #define PG8_STAGEB(bufoff, gbase, voff) do { _Pragma("unroll") for (int _i = 0; _i < 2; ++_i) \
;         __builtin_amdgcn_global_load_lds((const unsigned*)((const char*)(gbase) + (voff)[_i]), (PG8_LAS unsigned*)(lds + (bufoff) + ldsw + _i * 8192), 16, 0, AUX_B); } while (0)
; #define PG8_LDA(dst, b, h) do { _Pragma("unroll") for (int m = 0; m < 4; ++m) _Pragma("unroll") for (int k = 0; k < 2; ++k) dst[m][k] = *(const PG8_LAS bf16x8*)(lds + PG8_SA(b, h) + aoff + m * 2048 + k * 1024); } while (0)
; #define PG8_LDB(dst, b, h) do { _Pragma("unroll") for (int n = 0; n < 2; ++n) _Pragma("unroll") for (int k = 0; k < 2; ++k) dst[n][k] = *(const PG8_LAS bf16x8*)(lds + PG8_SB(b, h) + boff + n * 2048 + k * 1024); } while (0)
; #define PG8_MMA(ai, bj, At, Bt) do { __builtin_amdgcn_s_setprio(1); _Pragma("unroll") for (int m = 0; m < 4; ++m) _Pragma("unroll") for (int n = 0; n < 2; ++n) _Pragma("unroll") for (int k = 0; k < 2; ++k) \
;         acc[ai][bj][m][n] = __builtin_amdgcn_mfma_f32_16x16x32_bf16(Bt[n][k], At[m][k], acc[ai][bj][m][n], 0, 0, 0); __builtin_amdgcn_s_setprio(0); } while (0)
; #define PG8_WAIT_V(n) asm volatile("s_waitcnt vmcnt(" #n ")" ::: "memory")
; #define PG8_WAIT_L(n) asm volatile("s_waitcnt lgkmcnt(" #n ")" ::: "memory")
; #define PG8_BAR __builtin_amdgcn_s_barrier()
; #define PG8_SCHED __builtin_amdgcn_sched_barrier(0)
; template <class Epi, class Sched, bool ALIGN_EPI = false, bool SP2 = false>
; __device__ __forceinline__ void gemm_phase(PG8_LAS unsigned char* lds, const Gemm g, const Sched& S, const Epi& E) {
;     ...
;             PG8_LDB(B0, 1, 0); PG8_LDB(B1, 1, 1); PG8_SCHED; PG8_LDA(At, 1, 0); PG8_STAGE(PG8_SA(0, 1), a2 + hstep, voffA);
;             PG8_WAIT_V(8); PG8_WAIT_L(0); PG8_BAR; PG8_MMA(0, 0, At, B0); PG8_MMA(0, 1, At, B1); PG8_BAR; PG8_SCHED;
;             PG8_LDA(At, 1, 1); PG8_STAGEB(PG8_SB(1, 0), b3, voffB); PG8_STAGEB(PG8_SB(1, 1), b3 + hstep, voffB); PG8_STAGE(PG8_SA(1, 0), a3, voffA);
;             PG8_WAIT_V(8); PG8_WAIT_L(0); PG8_BAR; PG8_MMA(1, 0, At, B0); PG8_MMA(1, 1, At, B1); PG8_BAR; PG8_SCHED;
	v_mfma_f32_16x16x32_bf16 v[2:5], v[188:191], v[238:241], 0
	v_mfma_f32_16x16x32_bf16 v[2:5], v[192:195], v[242:245], v[2:5]
	s_setprio 0
	v_add_u32_e32 v162, vcc_lo, v99
	v_add_u32_e32 v192, vcc_hi, v99
	ds_read_b128 v[148:151], v162
	ds_read_b128 v[154:157], v162 offset:1024
	ds_read_b128 v[158:161], v162 offset:2048
	ds_read_b128 v[162:165], v162 offset:3072
	ds_read_b128 v[180:183], v192
	ds_read_b128 v[184:187], v192 offset:1024
	ds_read_b128 v[188:191], v192 offset:2048
	ds_read_b128 v[192:195], v192 offset:3072
	s_mov_b32 m0, s78
	v_lshl_add_u64 v[246:247], s[56:57], 0, v[138:139]
	ds_read_b128 v[196:199], v153 offset:32768
	ds_read_b128 v[200:203], v153 offset:33792
	ds_read_b128 v[222:225], v153 offset:34816
	ds_read_b128 v[226:229], v153 offset:35840
	ds_read_b128 v[230:233], v153 offset:36864
	ds_read_b128 v[234:237], v153 offset:37888
	ds_read_b128 v[238:241], v153 offset:38912
	ds_read_b128 v[242:245], v153 offset:39936
	global_load_lds_dwordx4 v[246:247], off
	v_lshl_add_u64 v[246:247], s[56:57], 0, v[134:135]
	s_mov_b32 m0, s82
	s_nop 0
	global_load_lds_dwordx4 v[246:247], off
	s_waitcnt vmcnt(8)
	s_waitcnt lgkmcnt(0)
	s_setprio 1
	s_barrier
	v_mfma_f32_16x16x32_bf16 v[128:131], v[148:151], v[196:199], v[128:131]
	v_mfma_f32_16x16x32_bf16 v[128:131], v[154:157], v[200:203], v[128:131]
	v_mfma_f32_16x16x32_bf16 v[124:127], v[158:161], v[196:199], v[124:127]
	v_mfma_f32_16x16x32_bf16 v[124:127], v[162:165], v[200:203], v[124:127]
	v_mfma_f32_16x16x32_bf16 v[112:115], v[148:151], v[222:225], v[112:115]
	v_mfma_f32_16x16x32_bf16 v[112:115], v[154:157], v[226:229], v[112:115]
	v_mfma_f32_16x16x32_bf16 v[108:111], v[158:161], v[222:225], v[108:111]
	v_mfma_f32_16x16x32_bf16 v[108:111], v[162:165], v[226:229], v[108:111]
	v_mfma_f32_16x16x32_bf16 v[94:97], v[148:151], v[230:233], v[94:97]
	v_mfma_f32_16x16x32_bf16 v[94:97], v[154:157], v[234:237], v[94:97]
	v_mfma_f32_16x16x32_bf16 v[90:93], v[158:161], v[230:233], v[90:93]
	v_mfma_f32_16x16x32_bf16 v[90:93], v[162:165], v[234:237], v[90:93]
	v_mfma_f32_16x16x32_bf16 v[78:81], v[148:151], v[238:241], v[78:81]
	v_mfma_f32_16x16x32_bf16 v[78:81], v[154:157], v[242:245], v[78:81]
	v_mfma_f32_16x16x32_bf16 v[74:77], v[158:161], v[238:241], v[74:77]
	v_mfma_f32_16x16x32_bf16 v[74:77], v[162:165], v[242:245], v[74:77]
	s_setprio 0
	s_setprio 1
	v_mfma_f32_16x16x32_bf16 v[120:123], v[180:183], v[196:199], v[120:123]
	v_mfma_f32_16x16x32_bf16 v[120:123], v[184:187], v[200:203], v[120:123]
	v_mfma_f32_16x16x32_bf16 v[116:119], v[188:191], v[196:199], v[116:119]
	v_mfma_f32_16x16x32_bf16 v[116:119], v[192:195], v[200:203], v[116:119]
	v_mfma_f32_16x16x32_bf16 v[104:107], v[180:183], v[222:225], v[104:107]
	v_mfma_f32_16x16x32_bf16 v[104:107], v[184:187], v[226:229], v[104:107]
	v_mfma_f32_16x16x32_bf16 v[100:103], v[188:191], v[222:225], v[100:103]
	v_mfma_f32_16x16x32_bf16 v[100:103], v[192:195], v[226:229], v[100:103]
	v_mfma_f32_16x16x32_bf16 v[86:89], v[180:183], v[230:233], v[86:89]
	v_mfma_f32_16x16x32_bf16 v[86:89], v[184:187], v[234:237], v[86:89]
	v_mfma_f32_16x16x32_bf16 v[82:85], v[188:191], v[230:233], v[82:85]
	v_mfma_f32_16x16x32_bf16 v[82:85], v[192:195], v[234:237], v[82:85]
	v_mfma_f32_16x16x32_bf16 v[70:73], v[180:183], v[238:241], v[70:73]
	v_mfma_f32_16x16x32_bf16 v[70:73], v[184:187], v[242:245], v[70:73]
	s_setprio 2
	s_barrier
	v_mfma_f32_16x16x32_bf16 v[66:69], v[188:191], v[238:241], v[66:69]
	v_mfma_f32_16x16x32_bf16 v[66:69], v[192:195], v[242:245], v[66:69]
	s_setprio 0
	s_mov_b32 m0, s1
	v_lshl_add_u64 v[166:167], v[166:167], 0, s[76:77]
	ds_read_b128 v[196:199], v153 offset:49152
	ds_read_b128 v[200:203], v153 offset:50176
	ds_read_b128 v[222:225], v153 offset:51200
	ds_read_b128 v[226:229], v153 offset:52224
	ds_read_b128 v[230:233], v153 offset:53248
	ds_read_b128 v[234:237], v153 offset:54272
	ds_read_b128 v[238:241], v153 offset:55296
	ds_read_b128 v[242:245], v153 offset:56320
	global_load_lds_dwordx4 v[166:167], off
	v_lshl_add_u64 v[166:167], v[168:169], 0, s[76:77]
	s_mov_b32 m0, s0
	s_nop 0
	global_load_lds_dwordx4 v[166:167], off
	v_lshl_add_u64 v[166:167], s[54:55], 0, v[136:137]
	s_mov_b32 m0, s47
	s_nop 0
	global_load_lds_dwordx4 v[166:167], off
	v_lshl_add_u64 v[166:167], s[54:55], 0, v[132:133]
	s_mov_b32 m0, s46
	s_nop 0
	global_load_lds_dwordx4 v[166:167], off
	v_lshl_add_u64 v[166:167], v[172:173], 0, s[76:77]
	s_mov_b32 m0, s83
	s_nop 0
	global_load_lds_dwordx4 v[166:167], off
	v_lshl_add_u64 v[166:167], v[212:213], 0, s[76:77]
	s_mov_b32 m0, s88
	s_nop 0
	global_load_lds_dwordx4 v[166:167], off
	s_waitcnt vmcnt(8)
	s_waitcnt lgkmcnt(0)
	s_setprio 1
	s_barrier
	v_mfma_f32_16x16x32_bf16 v[62:65], v[148:151], v[196:199], v[62:65]
	v_mfma_f32_16x16x32_bf16 v[62:65], v[154:157], v[200:203], v[62:65]
	v_mfma_f32_16x16x32_bf16 v[58:61], v[158:161], v[196:199], v[58:61]
	v_mfma_f32_16x16x32_bf16 v[58:61], v[162:165], v[200:203], v[58:61]
	v_mfma_f32_16x16x32_bf16 v[46:49], v[148:151], v[222:225], v[46:49]
	v_mfma_f32_16x16x32_bf16 v[46:49], v[154:157], v[226:229], v[46:49]
	v_mfma_f32_16x16x32_bf16 v[42:45], v[158:161], v[222:225], v[42:45]
	v_mfma_f32_16x16x32_bf16 v[42:45], v[162:165], v[226:229], v[42:45]
	v_mfma_f32_16x16x32_bf16 v[30:33], v[148:151], v[230:233], v[30:33]
	v_mfma_f32_16x16x32_bf16 v[30:33], v[154:157], v[234:237], v[30:33]
	v_mfma_f32_16x16x32_bf16 v[26:29], v[158:161], v[230:233], v[26:29]
	v_mfma_f32_16x16x32_bf16 v[26:29], v[162:165], v[234:237], v[26:29]
	v_mfma_f32_16x16x32_bf16 v[14:17], v[148:151], v[238:241], v[14:17]
	v_mfma_f32_16x16x32_bf16 v[14:17], v[154:157], v[242:245], v[14:17]
	v_mfma_f32_16x16x32_bf16 v[10:13], v[158:161], v[238:241], v[10:13]
	v_mfma_f32_16x16x32_bf16 v[10:13], v[162:165], v[242:245], v[10:13]
	s_setprio 0
	s_setprio 1
	v_mfma_f32_16x16x32_bf16 v[54:57], v[180:183], v[196:199], v[54:57]
	v_mfma_f32_16x16x32_bf16 v[54:57], v[184:187], v[200:203], v[54:57]
	v_mfma_f32_16x16x32_bf16 v[50:53], v[188:191], v[196:199], v[50:53]
	v_mfma_f32_16x16x32_bf16 v[50:53], v[192:195], v[200:203], v[50:53]
	v_mfma_f32_16x16x32_bf16 v[38:41], v[180:183], v[222:225], v[38:41]
	v_mfma_f32_16x16x32_bf16 v[38:41], v[184:187], v[226:229], v[38:41]
	v_mfma_f32_16x16x32_bf16 v[34:37], v[188:191], v[222:225], v[34:37]
	v_mfma_f32_16x16x32_bf16 v[34:37], v[192:195], v[226:229], v[34:37]
	v_mfma_f32_16x16x32_bf16 v[22:25], v[180:183], v[230:233], v[22:25]
	v_mfma_f32_16x16x32_bf16 v[22:25], v[184:187], v[234:237], v[22:25]
	v_mfma_f32_16x16x32_bf16 v[18:21], v[188:191], v[230:233], v[18:21]
	v_mfma_f32_16x16x32_bf16 v[18:21], v[192:195], v[234:237], v[18:21]
	v_mfma_f32_16x16x32_bf16 v[6:9], v[180:183], v[238:241], v[6:9]
	v_mfma_f32_16x16x32_bf16 v[6:9], v[184:187], v[242:245], v[6:9]
	s_setprio 2
	s_barrier
	v_mfma_f32_16x16x32_bf16 v[2:5], v[188:191], v[238:241], v[2:5]
	v_mfma_f32_16x16x32_bf16 v[2:5], v[192:195], v[242:245], v[2:5]
	s_setprio 0
	v_lshl_add_u64 v[144:145], v[144:145], 0, s[86:87]
	v_lshl_add_u64 v[146:147], v[146:147], 0, s[86:87]
	s_mov_b32 s29, s81
	s_cbranch_scc1 .Lpx_1157

; #define PG8_STAGE(bufoff, gbase, voff) do { _Pragma("unroll") for (int _i = 0; _i < 2; ++_i) \
;         __builtin_amdgcn_global_load_lds((const unsigned*)((const char*)(gbase) + (voff)[_i]), (PG8_LAS unsigned*)(lds + (bufoff) + ldsw + _i * 8192), 16, 0, AUX_A); } while (0)
; #define PG8_LDA(dst, b, h) do { _Pragma("unroll") for (int m = 0; m < 4; ++m) _Pragma("unroll") for (int k = 0; k < 2; ++k) dst[m][k] = *(const PG8_LAS bf16x8*)(lds + PG8_SA(b, h) + aoff + m * 2048 + k * 1024); } while (0)
; #define PG8_LDB(dst, b, h) do { _Pragma("unroll") for (int n = 0; n < 2; ++n) _Pragma("unroll") for (int k = 0; k < 2; ++k) dst[n][k] = *(const PG8_LAS bf16x8*)(lds + PG8_SB(b, h) + boff + n * 2048 + k * 1024); } while (0)
; #define PG8_SCHED __builtin_amdgcn_sched_barrier(0)
;     __host__ __device__ bool next(int i, Unit& u) const {
;         int e = i * G + c; if (e >= 512) return false;
;         if (SPLIT_SWAP && G == 256 && (c & 1)) e ^= 256;
;         const int f = e & 255, x = f & 7, j = f >> 3;
;         if (e < 256) { u.pm = 4 * x + (j >> 3); u.pn = j & 7; u.kt0 = 0; u.nkt = nkt; u.slab = -1; u.krot = KROT ? 2 * ((x * (nkt >> 1)) >> 3) : 0; }
;         else { const int np = nkt >> 1, base = np >> 3, rem = np & 7, pairs = base + (x < rem ? 1 : 0), start = x * base + (x < rem ? x : rem);
;             u.pm = 32 + (j >> 3); u.pn = j & 7; u.kt0 = 2 * start; u.nkt = 2 * pairs; u.slab = x; u.krot = 0; }
; template <class Epi, class Sched, bool ALIGN_EPI = false, bool SP2 = false>
; __device__ __forceinline__ void gemm_phase(PG8_LAS unsigned char* lds, const Gemm g, const Sched& S, const Epi& E) {
;     ...
;             PG8_LDB(B0, 0, 0); PG8_LDB(B1, 0, 1); PG8_SCHED; PG8_LDA(At, 0, 0); PG8_STAGE(PG8_SA(1, 1), a1 + hstep, voffA);
.LBB0_1297:
	v_add_u32_e32 v148, 0x10000, v99
	v_add_u32_e32 v168, 0x14000, v99
	ds_read_b128 v[136:139], v148
	ds_read_b128 v[140:143], v148 offset:1024
	ds_read_b128 v[144:147], v148 offset:2048
	ds_read_b128 v[148:151], v148 offset:3072
	ds_read_b128 v[164:167], v168
	ds_read_b128 v[182:185], v168 offset:1024
	ds_read_b128 v[186:189], v168 offset:2048
	ds_read_b128 v[190:193], v168 offset:3072
	ds_read_b128 v[194:197], v181
	ds_read_b128 v[198:201], v181 offset:1024
	ds_read_b128 v[222:225], v181 offset:2048
	ds_read_b128 v[226:229], v181 offset:3072
	ds_read_b128 v[230:233], v181 offset:4096
	ds_read_b128 v[234:237], v181 offset:5120
	ds_read_b128 v[238:241], v181 offset:6144
	ds_read_b128 v[242:245], v181 offset:7168
	s_add_i32 s61, s61, 1
	s_mul_i32 s0, s61, s68
	s_add_i32 s0, s0, s92
	s_cmpk_lt_i32 s0, 0x200
	s_cselect_b64 s[16:17], -1, 0
	s_cmpk_gt_i32 s0, 0x1ff
	s_cbranch_scc1 .LBB0_1303
	s_bfe_u32 s1, s0, 0x20006
	s_cmpk_gt_i32 s0, 0xff
	s_mov_b64 s[14:15], -1
	s_cbranch_scc0 .LBB0_1300
	s_or_b32 s10, s1, 32
	s_mov_b64 s[14:15], 0

; #define PG8_STAGE(bufoff, gbase, voff) do { _Pragma("unroll") for (int _i = 0; _i < 2; ++_i) \
;         __builtin_amdgcn_global_load_lds((const unsigned*)((const char*)(gbase) + (voff)[_i]), (PG8_LAS unsigned*)(lds + (bufoff) + ldsw + _i * 8192), 16, 0, AUX_A); } while (0)
; #define PG8_STAGEB(bufoff, gbase, voff) do { _Pragma("unroll") for (int _i = 0; _i < 2; ++_i) \
;         __builtin_amdgcn_global_load_lds((const unsigned*)((const char*)(gbase) + (voff)[_i]), (PG8_LAS unsigned*)(lds + (bufoff) + ldsw + _i * 8192), 16, 0, AUX_B); } while (0)
; #define PG8_LDA(dst, b, h) do { _Pragma("unroll") for (int m = 0; m < 4; ++m) _Pragma("unroll") for (int k = 0; k < 2; ++k) dst[m][k] = *(const PG8_LAS bf16x8*)(lds + PG8_SA(b, h) + aoff + m * 2048 + k * 1024); } while (0)
; #define PG8_LDB(dst, b, h) do { _Pragma("unroll") for (int n = 0; n < 2; ++n) _Pragma("unroll") for (int k = 0; k < 2; ++k) dst[n][k] = *(const PG8_LAS bf16x8*)(lds + PG8_SB(b, h) + boff + n * 2048 + k * 1024); } while (0)
; #define PG8_WAIT_V(n) asm volatile("s_waitcnt vmcnt(" #n ")" ::: "memory")
; #define PG8_WAIT_L(n) asm volatile("s_waitcnt lgkmcnt(" #n ")" ::: "memory")
; #define PG8_BAR __builtin_amdgcn_s_barrier()
; #define PG8_SCHED __builtin_amdgcn_sched_barrier(0)
; template <class Epi, class Sched, bool ALIGN_EPI = false, bool SP2 = false>
; __device__ __forceinline__ void gemm_phase(PG8_LAS unsigned char* lds, const Gemm g, const Sched& S, const Epi& E) {
;     ...
;             const char* a1 = PG8_KP(cA, t + 1, rot, nt);
;             const char* a2 = last ? nAr : PG8_KP(cA, t + 2, rot, nt); const char* b2 = last ? nBr : PG8_KP(cB, t + 2, rot, nt);
;             const char* a3 = a2 + kstep; const char* b3 = b2 + kstep;
;             if (last && has_next) S.a_ready(nxt);
;             if constexpr (SP2) {
;             PG8_LDB(B0, 0, 0); PG8_LDB(B1, 0, 1); PG8_SCHED; PG8_LDA(At, 0, 0); PG8_STAGE(PG8_SA(1, 1), a1 + hstep, voffA);
;             PG8_WAIT_V(8); PG8_WAIT_L(0); PG8_BAR; PG8_MMA(0, 0, At, B0); PG8_MMA(0, 1, At, B1); PG8_BAR; PG8_SCHED;
;             PG8_LDA(At, 0, 1); PG8_STAGEB(PG8_SB(0, 0), b2, voffB); PG8_STAGEB(PG8_SB(0, 1), b2 + hstep, voffB); PG8_STAGE(PG8_SA(0, 0), a2, voffA);
;             PG8_WAIT_V(8); PG8_WAIT_L(0); PG8_BAR; PG8_MMA(1, 0, At, B0); PG8_MMA(1, 1, At, B1); PG8_BAR; PG8_SCHED;
.Lrp_1308:
.Lpk_1308:
	s_or_b32 s0, s11, 1
	s_cmp_ge_i32 s0, s71
	s_cselect_b32 s2, s71, 0
	s_add_i32 s11, s11, 2
	s_cmp_ge_i32 s11, s71
	s_cselect_b32 s0, s71, 0
	s_sub_i32 s0, s13, s0
	s_ashr_i32 s1, s0, 31
	s_lshl_b64 s[0:1], s[0:1], 7
	s_add_u32 s15, s40, s0
	s_addc_u32 s29, s41, s1
	s_add_u32 s0, s34, s0
	s_addc_u32 s1, s35, s1
	s_cmp_eq_u32 s71, s13
	s_cselect_b32 s45, s43, s29
	s_cselect_b32 s44, s42, s15
	s_cselect_b32 s37, s19, s1
	s_cselect_b32 s36, s18, s0
	s_add_i32 s15, 0, 0x10000
	s_add_i32 s29, 0, 0x14000
	v_mad_i64_i32 v[168:169], s[0:1], s2, v220, v[134:135]
	s_add_i32 m0, s50, 0xc000
	global_load_lds_dwordx4 v[168:169], off
	v_mad_i64_i32 v[168:169], s[0:1], s2, v220, v[132:133]
	s_add_i32 m0, s50, 0xe000
	s_nop 0
	global_load_lds_dwordx4 v[168:169], off
	s_waitcnt vmcnt(8)
	s_waitcnt lgkmcnt(0)
	s_setprio 1
	s_barrier
	v_mfma_f32_16x16x32_bf16 v[128:131], v[136:139], v[194:197], 0
	v_mfma_f32_16x16x32_bf16 v[128:131], v[140:143], v[198:201], v[128:131]
	v_mfma_f32_16x16x32_bf16 v[124:127], v[144:147], v[194:197], 0
	v_mfma_f32_16x16x32_bf16 v[124:127], v[148:151], v[198:201], v[124:127]
	v_mfma_f32_16x16x32_bf16 v[120:123], v[136:139], v[222:225], 0
	v_mfma_f32_16x16x32_bf16 v[120:123], v[140:143], v[226:229], v[120:123]
	v_mfma_f32_16x16x32_bf16 v[112:115], v[144:147], v[222:225], 0
	v_mfma_f32_16x16x32_bf16 v[112:115], v[148:151], v[226:229], v[112:115]
	v_mfma_f32_16x16x32_bf16 v[104:107], v[136:139], v[230:233], 0
	v_mfma_f32_16x16x32_bf16 v[104:107], v[140:143], v[234:237], v[104:107]
	v_mfma_f32_16x16x32_bf16 v[94:97], v[144:147], v[230:233], 0
	v_mfma_f32_16x16x32_bf16 v[94:97], v[148:151], v[234:237], v[94:97]
	v_mfma_f32_16x16x32_bf16 v[86:89], v[136:139], v[238:241], 0
	v_mfma_f32_16x16x32_bf16 v[86:89], v[140:143], v[242:245], v[86:89]
	v_mfma_f32_16x16x32_bf16 v[78:81], v[144:147], v[238:241], 0
	v_mfma_f32_16x16x32_bf16 v[78:81], v[148:151], v[242:245], v[78:81]
	s_setprio 0
	s_setprio 1
	v_mfma_f32_16x16x32_bf16 v[116:119], v[164:167], v[194:197], 0
	v_mfma_f32_16x16x32_bf16 v[116:119], v[182:185], v[198:201], v[116:119]
	v_mfma_f32_16x16x32_bf16 v[108:111], v[186:189], v[194:197], 0
	v_mfma_f32_16x16x32_bf16 v[108:111], v[190:193], v[198:201], v[108:111]
	v_mfma_f32_16x16x32_bf16 v[100:103], v[164:167], v[222:225], 0
	v_mfma_f32_16x16x32_bf16 v[100:103], v[182:185], v[226:229], v[100:103]
	v_mfma_f32_16x16x32_bf16 v[90:93], v[186:189], v[222:225], 0
	v_mfma_f32_16x16x32_bf16 v[90:93], v[190:193], v[226:229], v[90:93]
	v_mfma_f32_16x16x32_bf16 v[82:85], v[164:167], v[230:233], 0
	v_mfma_f32_16x16x32_bf16 v[82:85], v[182:185], v[234:237], v[82:85]
	v_mfma_f32_16x16x32_bf16 v[74:77], v[186:189], v[230:233], 0
	v_mfma_f32_16x16x32_bf16 v[74:77], v[190:193], v[234:237], v[74:77]
	v_mfma_f32_16x16x32_bf16 v[70:73], v[164:167], v[238:241], 0
	v_mfma_f32_16x16x32_bf16 v[70:73], v[182:185], v[242:245], v[70:73]
	s_setprio 2
	s_barrier
	v_mfma_f32_16x16x32_bf16 v[66:69], v[186:189], v[238:241], 0
	v_mfma_f32_16x16x32_bf16 v[66:69], v[190:193], v[242:245], v[66:69]
	s_setprio 0
	s_add_i32 s0, s15, s49
	v_lshl_add_u64 v[168:169], s[36:37], 0, v[156:157]
	s_mov_b32 m0, s0
	ds_read_b128 v[194:197], v181 offset:16384
	ds_read_b128 v[198:201], v181 offset:17408
	ds_read_b128 v[222:225], v181 offset:18432
	ds_read_b128 v[226:229], v181 offset:19456
	ds_read_b128 v[230:233], v181 offset:20480
	ds_read_b128 v[234:237], v181 offset:21504
	ds_read_b128 v[238:241], v181 offset:22528
	ds_read_b128 v[242:245], v181 offset:23552
	global_load_lds_dwordx4 v[168:169], off
	s_add_i32 m0, s0, 0x2000
	s_add_u32 s0, s36, 0x80000
	v_lshl_add_u64 v[172:173], s[36:37], 0, v[152:153]
	s_addc_u32 s1, s37, 0
	s_add_i32 s2, s29, s49
	global_load_lds_dwordx4 v[172:173], off
	v_lshl_add_u64 v[202:203], s[0:1], 0, v[156:157]
	s_mov_b32 m0, s2
	v_lshl_add_u64 v[212:213], s[44:45], 0, v[154:155]
	global_load_lds_dwordx4 v[202:203], off
	v_lshl_add_u64 v[202:203], s[0:1], 0, v[152:153]
	s_add_i32 m0, s2, 0x2000
	s_nop 0
	global_load_lds_dwordx4 v[202:203], off
	v_lshl_add_u64 v[202:203], s[44:45], 0, v[158:159]
	s_mov_b32 m0, s50
	s_nop 0
	global_load_lds_dwordx4 v[202:203], off
	s_mov_b32 m0, s51
	s_nop 0
	global_load_lds_dwordx4 v[212:213], off
	s_waitcnt vmcnt(8)
	s_waitcnt lgkmcnt(0)
	s_setprio 1
	s_barrier
	v_mfma_f32_16x16x32_bf16 v[62:65], v[136:139], v[194:197], 0
	v_mfma_f32_16x16x32_bf16 v[62:65], v[140:143], v[198:201], v[62:65]
	v_mfma_f32_16x16x32_bf16 v[58:61], v[144:147], v[194:197], 0
	v_mfma_f32_16x16x32_bf16 v[58:61], v[148:151], v[198:201], v[58:61]
	v_mfma_f32_16x16x32_bf16 v[54:57], v[136:139], v[222:225], 0
	v_mfma_f32_16x16x32_bf16 v[54:57], v[140:143], v[226:229], v[54:57]
	v_mfma_f32_16x16x32_bf16 v[46:49], v[144:147], v[222:225], 0
	v_mfma_f32_16x16x32_bf16 v[46:49], v[148:151], v[226:229], v[46:49]
	v_mfma_f32_16x16x32_bf16 v[38:41], v[136:139], v[230:233], 0
	v_mfma_f32_16x16x32_bf16 v[38:41], v[140:143], v[234:237], v[38:41]
	v_mfma_f32_16x16x32_bf16 v[30:33], v[144:147], v[230:233], 0
	v_mfma_f32_16x16x32_bf16 v[30:33], v[148:151], v[234:237], v[30:33]
	v_mfma_f32_16x16x32_bf16 v[22:25], v[136:139], v[238:241], 0
	v_mfma_f32_16x16x32_bf16 v[22:25], v[140:143], v[242:245], v[22:25]
	v_mfma_f32_16x16x32_bf16 v[14:17], v[144:147], v[238:241], 0
	v_mfma_f32_16x16x32_bf16 v[14:17], v[148:151], v[242:245], v[14:17]
	s_setprio 0
	s_setprio 1
	v_mfma_f32_16x16x32_bf16 v[50:53], v[164:167], v[194:197], 0
	v_mfma_f32_16x16x32_bf16 v[50:53], v[182:185], v[198:201], v[50:53]
	v_mfma_f32_16x16x32_bf16 v[42:45], v[186:189], v[194:197], 0
	v_mfma_f32_16x16x32_bf16 v[42:45], v[190:193], v[198:201], v[42:45]
	v_mfma_f32_16x16x32_bf16 v[34:37], v[164:167], v[222:225], 0
	v_mfma_f32_16x16x32_bf16 v[34:37], v[182:185], v[226:229], v[34:37]
	v_mfma_f32_16x16x32_bf16 v[26:29], v[186:189], v[222:225], 0
	v_mfma_f32_16x16x32_bf16 v[26:29], v[190:193], v[226:229], v[26:29]
	v_mfma_f32_16x16x32_bf16 v[18:21], v[164:167], v[230:233], 0
	v_mfma_f32_16x16x32_bf16 v[18:21], v[182:185], v[234:237], v[18:21]
	v_mfma_f32_16x16x32_bf16 v[10:13], v[186:189], v[230:233], 0
	v_mfma_f32_16x16x32_bf16 v[10:13], v[190:193], v[234:237], v[10:13]
	v_mfma_f32_16x16x32_bf16 v[6:9], v[164:167], v[238:241], 0
	v_mfma_f32_16x16x32_bf16 v[6:9], v[182:185], v[242:245], v[6:9]
	s_setprio 2
	s_barrier
; #define PG8_STAGE(bufoff, gbase, voff) do { _Pragma("unroll") for (int _i = 0; _i < 2; ++_i) \
;         __builtin_amdgcn_global_load_lds((const unsigned*)((const char*)(gbase) + (voff)[_i]), (PG8_LAS unsigned*)(lds + (bufoff) + ldsw + _i * 8192), 16, 0, AUX_A); } while (0)
; #define PG8_LDA(dst, b, h) do { _Pragma("unroll") for (int m = 0; m < 4; ++m) _Pragma("unroll") for (int k = 0; k < 2; ++k) dst[m][k] = *(const PG8_LAS bf16x8*)(lds + PG8_SA(b, h) + aoff + m * 2048 + k * 1024); } while (0)
; #define PG8_LDB(dst, b, h) do { _Pragma("unroll") for (int n = 0; n < 2; ++n) _Pragma("unroll") for (int k = 0; k < 2; ++k) dst[n][k] = *(const PG8_LAS bf16x8*)(lds + PG8_SB(b, h) + boff + n * 2048 + k * 1024); } while (0)
; #define PG8_MMA(ai, bj, At, Bt) do { __builtin_amdgcn_s_setprio(1); _Pragma("unroll") for (int m = 0; m < 4; ++m) _Pragma("unroll") for (int n = 0; n < 2; ++n) _Pragma("unroll") for (int k = 0; k < 2; ++k) \
;         acc[ai][bj][m][n] = __builtin_amdgcn_mfma_f32_16x16x32_bf16(Bt[n][k], At[m][k], acc[ai][bj][m][n], 0, 0, 0); __builtin_amdgcn_s_setprio(0); } while (0)
; #define PG8_WAIT_V(n) asm volatile("s_waitcnt vmcnt(" #n ")" ::: "memory")
; #define PG8_WAIT_L(n) asm volatile("s_waitcnt lgkmcnt(" #n ")" ::: "memory")
; #define PG8_BAR __builtin_amdgcn_s_barrier()
; #define PG8_SCHED __builtin_amdgcn_sched_barrier(0)
; template <class Epi, class Sched, bool ALIGN_EPI = false, bool SP2 = false>
; __device__ __forceinline__ void gemm_phase(PG8_LAS unsigned char* lds, const Gemm g, const Sched& S, const Epi& E) {
;     ...
;             PG8_LDB(B0, 1, 0); PG8_LDB(B1, 1, 1); PG8_SCHED; PG8_LDA(At, 1, 0); PG8_STAGE(PG8_SA(0, 1), a2 + hstep, voffA);
;             PG8_WAIT_V(8); PG8_WAIT_L(0); PG8_BAR; PG8_MMA(0, 0, At, B0); PG8_MMA(0, 1, At, B1); PG8_BAR; PG8_SCHED;
	v_mfma_f32_16x16x32_bf16 v[2:5], v[186:189], v[238:241], 0
	v_mfma_f32_16x16x32_bf16 v[2:5], v[190:193], v[242:245], v[2:5]
	s_setprio 0
	s_add_i32 s2, 0, 0x18000
	s_add_i32 s15, 0, 0x1c000
	v_add_u32_e32 v148, s2, v99
	v_add_u32_e32 v190, s15, v99
	ds_read_b128 v[136:139], v148
	ds_read_b128 v[140:143], v148 offset:1024
	ds_read_b128 v[144:147], v148 offset:2048
	ds_read_b128 v[148:151], v148 offset:3072
	ds_read_b128 v[164:167], v190
	ds_read_b128 v[182:185], v190 offset:1024
	ds_read_b128 v[186:189], v190 offset:2048
	ds_read_b128 v[190:193], v190 offset:3072
	s_add_u32 s0, s44, 0x80000
	s_addc_u32 s1, s45, 0
	s_mov_b32 m0, s52
	v_lshl_add_u64 v[246:247], s[0:1], 0, v[158:159]
	ds_read_b128 v[194:197], v181 offset:32768
	ds_read_b128 v[198:201], v181 offset:33792
	ds_read_b128 v[222:225], v181 offset:34816
	ds_read_b128 v[226:229], v181 offset:35840
	ds_read_b128 v[230:233], v181 offset:36864
	ds_read_b128 v[234:237], v181 offset:37888
	ds_read_b128 v[238:241], v181 offset:38912
	ds_read_b128 v[242:245], v181 offset:39936
	global_load_lds_dwordx4 v[246:247], off
	v_lshl_add_u64 v[246:247], s[0:1], 0, v[154:155]
	s_mov_b32 m0, s53
	s_nop 0
	global_load_lds_dwordx4 v[246:247], off
	s_waitcnt vmcnt(8)
	s_waitcnt lgkmcnt(0)
	s_setprio 1
	s_barrier
	v_mfma_f32_16x16x32_bf16 v[128:131], v[136:139], v[194:197], v[128:131]
	v_mfma_f32_16x16x32_bf16 v[128:131], v[140:143], v[198:201], v[128:131]
	v_mfma_f32_16x16x32_bf16 v[124:127], v[144:147], v[194:197], v[124:127]
	v_mfma_f32_16x16x32_bf16 v[124:127], v[148:151], v[198:201], v[124:127]
	v_mfma_f32_16x16x32_bf16 v[120:123], v[136:139], v[222:225], v[120:123]
	v_mfma_f32_16x16x32_bf16 v[120:123], v[140:143], v[226:229], v[120:123]
	v_mfma_f32_16x16x32_bf16 v[112:115], v[144:147], v[222:225], v[112:115]
	v_mfma_f32_16x16x32_bf16 v[112:115], v[148:151], v[226:229], v[112:115]
	v_mfma_f32_16x16x32_bf16 v[104:107], v[136:139], v[230:233], v[104:107]
	v_mfma_f32_16x16x32_bf16 v[104:107], v[140:143], v[234:237], v[104:107]
	v_mfma_f32_16x16x32_bf16 v[94:97], v[144:147], v[230:233], v[94:97]
	v_mfma_f32_16x16x32_bf16 v[94:97], v[148:151], v[234:237], v[94:97]
	v_mfma_f32_16x16x32_bf16 v[86:89], v[136:139], v[238:241], v[86:89]
	v_mfma_f32_16x16x32_bf16 v[86:89], v[140:143], v[242:245], v[86:89]
	v_mfma_f32_16x16x32_bf16 v[78:81], v[144:147], v[238:241], v[78:81]
	v_mfma_f32_16x16x32_bf16 v[78:81], v[148:151], v[242:245], v[78:81]
	s_setprio 0
	s_setprio 1
	v_mfma_f32_16x16x32_bf16 v[116:119], v[164:167], v[194:197], v[116:119]
	v_mfma_f32_16x16x32_bf16 v[116:119], v[182:185], v[198:201], v[116:119]
	v_mfma_f32_16x16x32_bf16 v[108:111], v[186:189], v[194:197], v[108:111]
	v_mfma_f32_16x16x32_bf16 v[108:111], v[190:193], v[198:201], v[108:111]
	v_mfma_f32_16x16x32_bf16 v[100:103], v[164:167], v[222:225], v[100:103]
	v_mfma_f32_16x16x32_bf16 v[100:103], v[182:185], v[226:229], v[100:103]
	v_mfma_f32_16x16x32_bf16 v[90:93], v[186:189], v[222:225], v[90:93]
	v_mfma_f32_16x16x32_bf16 v[90:93], v[190:193], v[226:229], v[90:93]
	v_mfma_f32_16x16x32_bf16 v[82:85], v[164:167], v[230:233], v[82:85]
	v_mfma_f32_16x16x32_bf16 v[82:85], v[182:185], v[234:237], v[82:85]
	v_mfma_f32_16x16x32_bf16 v[74:77], v[186:189], v[230:233], v[74:77]
	v_mfma_f32_16x16x32_bf16 v[74:77], v[190:193], v[234:237], v[74:77]
	v_mfma_f32_16x16x32_bf16 v[70:73], v[164:167], v[238:241], v[70:73]
	v_mfma_f32_16x16x32_bf16 v[70:73], v[182:185], v[242:245], v[70:73]
	s_setprio 2
	s_barrier
; #define PG8_STAGE(bufoff, gbase, voff) do { _Pragma("unroll") for (int _i = 0; _i < 2; ++_i) \
;         __builtin_amdgcn_global_load_lds((const unsigned*)((const char*)(gbase) + (voff)[_i]), (PG8_LAS unsigned*)(lds + (bufoff) + ldsw + _i * 8192), 16, 0, AUX_A); } while (0)
; #define PG8_STAGEB(bufoff, gbase, voff) do { _Pragma("unroll") for (int _i = 0; _i < 2; ++_i) \
;         __builtin_amdgcn_global_load_lds((const unsigned*)((const char*)(gbase) + (voff)[_i]), (PG8_LAS unsigned*)(lds + (bufoff) + ldsw + _i * 8192), 16, 0, AUX_B); } while (0)
; #define PG8_LDA(dst, b, h) do { _Pragma("unroll") for (int m = 0; m < 4; ++m) _Pragma("unroll") for (int k = 0; k < 2; ++k) dst[m][k] = *(const PG8_LAS bf16x8*)(lds + PG8_SA(b, h) + aoff + m * 2048 + k * 1024); } while (0)
; #define PG8_MMA(ai, bj, At, Bt) do { __builtin_amdgcn_s_setprio(1); _Pragma("unroll") for (int m = 0; m < 4; ++m) _Pragma("unroll") for (int n = 0; n < 2; ++n) _Pragma("unroll") for (int k = 0; k < 2; ++k) \
;         acc[ai][bj][m][n] = __builtin_amdgcn_mfma_f32_16x16x32_bf16(Bt[n][k], At[m][k], acc[ai][bj][m][n], 0, 0, 0); __builtin_amdgcn_s_setprio(0); } while (0)
; #define PG8_WAIT_V(n) asm volatile("s_waitcnt vmcnt(" #n ")" ::: "memory")
; #define PG8_WAIT_L(n) asm volatile("s_waitcnt lgkmcnt(" #n ")" ::: "memory")
; #define PG8_BAR __builtin_amdgcn_s_barrier()
; #define PG8_SCHED __builtin_amdgcn_sched_barrier(0)
; template <class Epi, class Sched, bool ALIGN_EPI = false, bool SP2 = false>
; __device__ __forceinline__ void gemm_phase(PG8_LAS unsigned char* lds, const Gemm g, const Sched& S, const Epi& E) {
;     ...
;             PG8_LDA(At, 1, 1); PG8_STAGEB(PG8_SB(1, 0), b3, voffB); PG8_STAGEB(PG8_SB(1, 1), b3 + hstep, voffB); PG8_STAGE(PG8_SA(1, 0), a3, voffA);
;             PG8_WAIT_V(8); PG8_WAIT_L(0); PG8_BAR; PG8_MMA(1, 0, At, B0); PG8_MMA(1, 1, At, B1); PG8_BAR; PG8_SCHED;
	v_mfma_f32_16x16x32_bf16 v[66:69], v[186:189], v[238:241], v[66:69]
	v_mfma_f32_16x16x32_bf16 v[66:69], v[190:193], v[242:245], v[66:69]
	s_setprio 0
	s_add_i32 s0, s2, s49
	v_lshl_add_u64 v[168:169], v[168:169], 0, s[76:77]
	s_mov_b32 m0, s0
	ds_read_b128 v[194:197], v181 offset:49152
	ds_read_b128 v[198:201], v181 offset:50176
	ds_read_b128 v[222:225], v181 offset:51200
	ds_read_b128 v[226:229], v181 offset:52224
	ds_read_b128 v[230:233], v181 offset:53248
	ds_read_b128 v[234:237], v181 offset:54272
	ds_read_b128 v[238:241], v181 offset:55296
	ds_read_b128 v[242:245], v181 offset:56320
	global_load_lds_dwordx4 v[168:169], off
	s_add_i32 m0, s0, 0x2000
	s_add_u32 s0, s36, 0x80080
	v_lshl_add_u64 v[168:169], v[172:173], 0, s[76:77]
	s_addc_u32 s1, s37, 0
	s_add_i32 s2, s15, s49
	global_load_lds_dwordx4 v[168:169], off
	v_lshl_add_u64 v[168:169], s[0:1], 0, v[156:157]
	s_mov_b32 m0, s2
	s_nop 0
	global_load_lds_dwordx4 v[168:169], off
	v_lshl_add_u64 v[168:169], s[0:1], 0, v[152:153]
	s_add_i32 m0, s2, 0x2000
	s_nop 0
	global_load_lds_dwordx4 v[168:169], off
	v_lshl_add_u64 v[168:169], v[202:203], 0, s[76:77]
	s_mov_b32 m0, s59
	s_nop 0
	global_load_lds_dwordx4 v[168:169], off
	v_lshl_add_u64 v[168:169], v[212:213], 0, s[76:77]
	s_mov_b32 m0, s60
	s_nop 0
	global_load_lds_dwordx4 v[168:169], off
	s_waitcnt vmcnt(8)
	s_waitcnt lgkmcnt(0)
	s_setprio 1
	s_barrier
	v_mfma_f32_16x16x32_bf16 v[62:65], v[136:139], v[194:197], v[62:65]
	v_mfma_f32_16x16x32_bf16 v[62:65], v[140:143], v[198:201], v[62:65]
	v_mfma_f32_16x16x32_bf16 v[58:61], v[144:147], v[194:197], v[58:61]
	v_mfma_f32_16x16x32_bf16 v[58:61], v[148:151], v[198:201], v[58:61]
	v_mfma_f32_16x16x32_bf16 v[54:57], v[136:139], v[222:225], v[54:57]
	v_mfma_f32_16x16x32_bf16 v[54:57], v[140:143], v[226:229], v[54:57]
	v_mfma_f32_16x16x32_bf16 v[46:49], v[144:147], v[222:225], v[46:49]
	v_mfma_f32_16x16x32_bf16 v[46:49], v[148:151], v[226:229], v[46:49]
	v_mfma_f32_16x16x32_bf16 v[38:41], v[136:139], v[230:233], v[38:41]
	v_mfma_f32_16x16x32_bf16 v[38:41], v[140:143], v[234:237], v[38:41]
	v_mfma_f32_16x16x32_bf16 v[30:33], v[144:147], v[230:233], v[30:33]
	v_mfma_f32_16x16x32_bf16 v[30:33], v[148:151], v[234:237], v[30:33]
	v_mfma_f32_16x16x32_bf16 v[22:25], v[136:139], v[238:241], v[22:25]
	v_mfma_f32_16x16x32_bf16 v[22:25], v[140:143], v[242:245], v[22:25]
	v_mfma_f32_16x16x32_bf16 v[14:17], v[144:147], v[238:241], v[14:17]
	v_mfma_f32_16x16x32_bf16 v[14:17], v[148:151], v[242:245], v[14:17]
	s_setprio 0
	s_setprio 1
	v_mfma_f32_16x16x32_bf16 v[50:53], v[164:167], v[194:197], v[50:53]
	v_mfma_f32_16x16x32_bf16 v[50:53], v[182:185], v[198:201], v[50:53]
	v_mfma_f32_16x16x32_bf16 v[42:45], v[186:189], v[194:197], v[42:45]
	v_mfma_f32_16x16x32_bf16 v[42:45], v[190:193], v[198:201], v[42:45]
	v_mfma_f32_16x16x32_bf16 v[34:37], v[164:167], v[222:225], v[34:37]
	v_mfma_f32_16x16x32_bf16 v[34:37], v[182:185], v[226:229], v[34:37]
	v_mfma_f32_16x16x32_bf16 v[26:29], v[186:189], v[222:225], v[26:29]
	v_mfma_f32_16x16x32_bf16 v[26:29], v[190:193], v[226:229], v[26:29]
	v_mfma_f32_16x16x32_bf16 v[18:21], v[164:167], v[230:233], v[18:21]
	v_mfma_f32_16x16x32_bf16 v[18:21], v[182:185], v[234:237], v[18:21]
	v_mfma_f32_16x16x32_bf16 v[10:13], v[186:189], v[230:233], v[10:13]
	v_mfma_f32_16x16x32_bf16 v[10:13], v[190:193], v[234:237], v[10:13]
	v_mfma_f32_16x16x32_bf16 v[6:9], v[164:167], v[238:241], v[6:9]
	v_mfma_f32_16x16x32_bf16 v[6:9], v[182:185], v[242:245], v[6:9]
	s_setprio 2
	s_barrier
	v_mfma_f32_16x16x32_bf16 v[2:5], v[186:189], v[238:241], v[2:5]
	v_mfma_f32_16x16x32_bf16 v[2:5], v[190:193], v[242:245], v[2:5]
	s_setprio 0
	s_add_i32 s0, s13, 2
	v_lshl_add_u64 v[132:133], v[132:133], 0, s[86:87]
	v_lshl_add_u64 v[134:135], v[134:135], 0, s[86:87]
	s_cmp_ge_i32 s13, s71
	s_mov_b32 s13, s0
	s_cbranch_scc1 .Lpx_1308

; #define PG8_STAGE(bufoff, gbase, voff) do { _Pragma("unroll") for (int _i = 0; _i < 2; ++_i) \
;         __builtin_amdgcn_global_load_lds((const unsigned*)((const char*)(gbase) + (voff)[_i]), (PG8_LAS unsigned*)(lds + (bufoff) + ldsw + _i * 8192), 16, 0, AUX_A); } while (0)
; #define PG8_LDA(dst, b, h) do { _Pragma("unroll") for (int m = 0; m < 4; ++m) _Pragma("unroll") for (int k = 0; k < 2; ++k) dst[m][k] = *(const PG8_LAS bf16x8*)(lds + PG8_SA(b, h) + aoff + m * 2048 + k * 1024); } while (0)
; #define PG8_LDB(dst, b, h) do { _Pragma("unroll") for (int n = 0; n < 2; ++n) _Pragma("unroll") for (int k = 0; k < 2; ++k) dst[n][k] = *(const PG8_LAS bf16x8*)(lds + PG8_SB(b, h) + boff + n * 2048 + k * 1024); } while (0)
; #define PG8_SCHED __builtin_amdgcn_sched_barrier(0)
;     __host__ __device__ bool next(int i, Unit& u) const {
;         int e = i * G + c; if (e >= 512) return false;
;         if (SPLIT_SWAP && G == 256 && (c & 1)) e ^= 256;
;         const int f = e & 255, x = f & 7, j = f >> 3;
;         if (e < 256) { u.pm = 4 * x + (j >> 3); u.pn = j & 7; u.kt0 = 0; u.nkt = nkt; u.slab = -1; u.krot = KROT ? 2 * ((x * (nkt >> 1)) >> 3) : 0; }
;         else { const int np = nkt >> 1, base = np >> 3, rem = np & 7, pairs = base + (x < rem ? 1 : 0), start = x * base + (x < rem ? x : rem);
;             u.pm = 32 + (j >> 3); u.pn = j & 7; u.kt0 = 2 * start; u.nkt = 2 * pairs; u.slab = x; u.krot = 0; }
; template <class Epi, class Sched, bool ALIGN_EPI = false, bool SP2 = false>
; __device__ __forceinline__ void gemm_phase(PG8_LAS unsigned char* lds, const Gemm g, const Sched& S, const Epi& E) {
;     ...
;             PG8_LDB(B0, 0, 0); PG8_LDB(B1, 0, 1); PG8_SCHED; PG8_LDA(At, 0, 0); PG8_STAGE(PG8_SA(1, 1), a1 + hstep, voffA);
.LBB0_1644:
	v_add_u32_e32 v148, 0x10000, v99
	v_add_u32_e32 v168, 0x14000, v99
	ds_read_b128 v[136:139], v148
	ds_read_b128 v[140:143], v148 offset:1024
	ds_read_b128 v[144:147], v148 offset:2048
	ds_read_b128 v[148:151], v148 offset:3072
	ds_read_b128 v[152:155], v168
	ds_read_b128 v[180:183], v168 offset:1024
	ds_read_b128 v[184:187], v168 offset:2048
	ds_read_b128 v[190:193], v168 offset:3072
	ds_read_b128 v[194:197], v189
	ds_read_b128 v[198:201], v189 offset:1024
	ds_read_b128 v[222:225], v189 offset:2048
	ds_read_b128 v[226:229], v189 offset:3072
	ds_read_b128 v[230:233], v189 offset:4096
	ds_read_b128 v[234:237], v189 offset:5120
	ds_read_b128 v[238:241], v189 offset:6144
	ds_read_b128 v[242:245], v189 offset:7168
	s_add_i32 s54, s54, 1
	s_mul_i32 s0, s54, s68
	s_add_i32 s0, s0, s92
	s_cmpk_lt_i32 s0, 0x200
	s_cselect_b64 s[16:17], -1, 0
	s_cmpk_gt_i32 s0, 0x1ff
	s_cbranch_scc1 .LBB0_1649
	s_and_b32 s62, s0, 7
	s_bfe_u32 s1, s0, 0x50003
	s_cmpk_gt_i32 s0, 0xff
	s_mov_b64 s[18:19], -1
	s_cbranch_scc0 .LBB0_1647
	s_cmp_lt_u32 s62, 4
	s_cselect_b32 s63, 12, 10
	s_mul_i32 s2, s62, 5
	s_min_u32 s14, s62, 4
	s_add_i32 s14, s14, s2
	s_lshr_b32 s2, s1, 3
	s_or_b32 s69, s2, 32
	s_bfe_u32 s70, s0, 0x30003
	s_lshl_b32 s14, s14, 1
	s_mov_b64 s[18:19], 0

; #define PG8_STAGE(bufoff, gbase, voff) do { _Pragma("unroll") for (int _i = 0; _i < 2; ++_i) \
;         __builtin_amdgcn_global_load_lds((const unsigned*)((const char*)(gbase) + (voff)[_i]), (PG8_LAS unsigned*)(lds + (bufoff) + ldsw + _i * 8192), 16, 0, AUX_A); } while (0)
; #define PG8_STAGEB(bufoff, gbase, voff) do { _Pragma("unroll") for (int _i = 0; _i < 2; ++_i) \
;         __builtin_amdgcn_global_load_lds((const unsigned*)((const char*)(gbase) + (voff)[_i]), (PG8_LAS unsigned*)(lds + (bufoff) + ldsw + _i * 8192), 16, 0, AUX_B); } while (0)
; #define PG8_LDA(dst, b, h) do { _Pragma("unroll") for (int m = 0; m < 4; ++m) _Pragma("unroll") for (int k = 0; k < 2; ++k) dst[m][k] = *(const PG8_LAS bf16x8*)(lds + PG8_SA(b, h) + aoff + m * 2048 + k * 1024); } while (0)
; #define PG8_LDB(dst, b, h) do { _Pragma("unroll") for (int n = 0; n < 2; ++n) _Pragma("unroll") for (int k = 0; k < 2; ++k) dst[n][k] = *(const PG8_LAS bf16x8*)(lds + PG8_SB(b, h) + boff + n * 2048 + k * 1024); } while (0)
; #define PG8_WAIT_V(n) asm volatile("s_waitcnt vmcnt(" #n ")" ::: "memory")
; #define PG8_WAIT_L(n) asm volatile("s_waitcnt lgkmcnt(" #n ")" ::: "memory")
; #define PG8_BAR __builtin_amdgcn_s_barrier()
; #define PG8_SCHED __builtin_amdgcn_sched_barrier(0)
; template <class Epi, class Sched, bool ALIGN_EPI = false, bool SP2 = false>
; __device__ __forceinline__ void gemm_phase(PG8_LAS unsigned char* lds, const Gemm g, const Sched& S, const Epi& E) {
;     ...
;             const char* a1 = PG8_KP(cA, t + 1, rot, nt);
;             const char* a2 = last ? nAr : PG8_KP(cA, t + 2, rot, nt); const char* b2 = last ? nBr : PG8_KP(cB, t + 2, rot, nt);
;             const char* a3 = a2 + kstep; const char* b3 = b2 + kstep;
;             if (last && has_next) S.a_ready(nxt);
;             if constexpr (SP2) {
;             PG8_LDB(B0, 0, 0); PG8_LDB(B1, 0, 1); PG8_SCHED; PG8_LDA(At, 0, 0); PG8_STAGE(PG8_SA(1, 1), a1 + hstep, voffA);
;             PG8_WAIT_V(8); PG8_WAIT_L(0); PG8_BAR; PG8_MMA(0, 0, At, B0); PG8_MMA(0, 1, At, B1); PG8_BAR; PG8_SCHED;
;             PG8_LDA(At, 0, 1); PG8_STAGEB(PG8_SB(0, 0), b2, voffB); PG8_STAGEB(PG8_SB(0, 1), b2 + hstep, voffB); PG8_STAGE(PG8_SA(0, 0), a2, voffA);
;             PG8_WAIT_V(8); PG8_WAIT_L(0); PG8_BAR; PG8_MMA(1, 0, At, B0); PG8_MMA(1, 1, At, B1); PG8_BAR; PG8_SCHED;
.Lrp_1654:
.Lpk_1654:
	s_or_b32 s0, s15, 1
	s_cmp_ge_i32 s0, s82
	s_cselect_b32 s2, s82, 0
	s_add_i32 s15, s15, 2
	s_cmp_ge_i32 s15, s82
	s_cselect_b32 s0, s82, 0
	s_sub_i32 s0, s83, s0
	s_ashr_i32 s1, s0, 31
	s_lshl_b64 s[0:1], s[0:1], 7
	s_add_u32 s29, s38, s0
	s_addc_u32 s42, s39, s1
	s_add_u32 s0, s34, s0
	s_addc_u32 s1, s35, s1
	s_cmp_eq_u32 s82, s83
	s_cselect_b32 s45, s41, s42
	s_cselect_b32 s44, s40, s29
	s_cselect_b32 s43, s19, s1
	s_cselect_b32 s42, s18, s0
	s_add_i32 s29, 0, 0x10000
	s_add_i32 s46, 0, 0x14000
	v_mad_i64_i32 v[168:169], s[0:1], s2, v220, v[134:135]
	s_add_i32 m0, s50, 0xc000
	global_load_lds_dwordx4 v[168:169], off
	v_mad_i64_i32 v[168:169], s[0:1], s2, v220, v[132:133]
	s_add_i32 m0, s50, 0xe000
	s_nop 0
	global_load_lds_dwordx4 v[168:169], off
	s_waitcnt vmcnt(8)
	s_waitcnt lgkmcnt(0)
	s_setprio 1
	s_barrier
	v_mfma_f32_16x16x32_bf16 v[128:131], v[136:139], v[194:197], 0
	v_mfma_f32_16x16x32_bf16 v[128:131], v[140:143], v[198:201], v[128:131]
	v_mfma_f32_16x16x32_bf16 v[124:127], v[144:147], v[194:197], 0
	v_mfma_f32_16x16x32_bf16 v[124:127], v[148:151], v[198:201], v[124:127]
	v_mfma_f32_16x16x32_bf16 v[120:123], v[136:139], v[222:225], 0
	v_mfma_f32_16x16x32_bf16 v[120:123], v[140:143], v[226:229], v[120:123]
	v_mfma_f32_16x16x32_bf16 v[112:115], v[144:147], v[222:225], 0
	v_mfma_f32_16x16x32_bf16 v[112:115], v[148:151], v[226:229], v[112:115]
	v_mfma_f32_16x16x32_bf16 v[104:107], v[136:139], v[230:233], 0
	v_mfma_f32_16x16x32_bf16 v[104:107], v[140:143], v[234:237], v[104:107]
	v_mfma_f32_16x16x32_bf16 v[94:97], v[144:147], v[230:233], 0
	v_mfma_f32_16x16x32_bf16 v[94:97], v[148:151], v[234:237], v[94:97]
	v_mfma_f32_16x16x32_bf16 v[86:89], v[136:139], v[238:241], 0
	v_mfma_f32_16x16x32_bf16 v[86:89], v[140:143], v[242:245], v[86:89]
	v_mfma_f32_16x16x32_bf16 v[78:81], v[144:147], v[238:241], 0
	v_mfma_f32_16x16x32_bf16 v[78:81], v[148:151], v[242:245], v[78:81]
	s_setprio 0
	s_setprio 1
	v_mfma_f32_16x16x32_bf16 v[116:119], v[152:155], v[194:197], 0
	v_mfma_f32_16x16x32_bf16 v[116:119], v[180:183], v[198:201], v[116:119]
	v_mfma_f32_16x16x32_bf16 v[108:111], v[184:187], v[194:197], 0
	v_mfma_f32_16x16x32_bf16 v[108:111], v[190:193], v[198:201], v[108:111]
	v_mfma_f32_16x16x32_bf16 v[100:103], v[152:155], v[222:225], 0
	v_mfma_f32_16x16x32_bf16 v[100:103], v[180:183], v[226:229], v[100:103]
	v_mfma_f32_16x16x32_bf16 v[90:93], v[184:187], v[222:225], 0
	v_mfma_f32_16x16x32_bf16 v[90:93], v[190:193], v[226:229], v[90:93]
	v_mfma_f32_16x16x32_bf16 v[82:85], v[152:155], v[230:233], 0
	v_mfma_f32_16x16x32_bf16 v[82:85], v[180:183], v[234:237], v[82:85]
	v_mfma_f32_16x16x32_bf16 v[74:77], v[184:187], v[230:233], 0
	v_mfma_f32_16x16x32_bf16 v[74:77], v[190:193], v[234:237], v[74:77]
	v_mfma_f32_16x16x32_bf16 v[70:73], v[152:155], v[238:241], 0
	v_mfma_f32_16x16x32_bf16 v[70:73], v[180:183], v[242:245], v[70:73]
	s_setprio 2
	s_barrier
	v_mfma_f32_16x16x32_bf16 v[66:69], v[184:187], v[238:241], 0
	v_mfma_f32_16x16x32_bf16 v[66:69], v[190:193], v[242:245], v[66:69]
	s_setprio 0
	s_add_i32 s0, s29, s49
	v_lshl_add_u64 v[168:169], s[42:43], 0, v[160:161]
	s_mov_b32 m0, s0
	ds_read_b128 v[194:197], v189 offset:16384
	ds_read_b128 v[198:201], v189 offset:17408
	ds_read_b128 v[222:225], v189 offset:18432
	ds_read_b128 v[226:229], v189 offset:19456
	ds_read_b128 v[230:233], v189 offset:20480
	ds_read_b128 v[234:237], v189 offset:21504
	ds_read_b128 v[238:241], v189 offset:22528
	ds_read_b128 v[242:245], v189 offset:23552
	global_load_lds_dwordx4 v[168:169], off
	s_add_i32 m0, s0, 0x2000
	s_add_u32 s0, s42, 0x160000
	v_lshl_add_u64 v[172:173], s[42:43], 0, v[156:157]
	s_addc_u32 s1, s43, 0
	s_add_i32 s2, s46, s49
	global_load_lds_dwordx4 v[172:173], off
	v_lshl_add_u64 v[202:203], s[0:1], 0, v[160:161]
	s_mov_b32 m0, s2
	v_lshl_add_u64 v[212:213], s[44:45], 0, v[158:159]
	global_load_lds_dwordx4 v[202:203], off
	v_lshl_add_u64 v[202:203], s[0:1], 0, v[156:157]
	s_add_i32 m0, s2, 0x2000
	s_nop 0
	global_load_lds_dwordx4 v[202:203], off
	v_lshl_add_u64 v[202:203], s[44:45], 0, v[162:163]
	s_mov_b32 m0, s50
	s_nop 0
	global_load_lds_dwordx4 v[202:203], off
	s_mov_b32 m0, s51
	s_nop 0
	global_load_lds_dwordx4 v[212:213], off
	s_waitcnt vmcnt(8)
	s_waitcnt lgkmcnt(0)
	s_setprio 1
	s_barrier
	v_mfma_f32_16x16x32_bf16 v[62:65], v[136:139], v[194:197], 0
	v_mfma_f32_16x16x32_bf16 v[62:65], v[140:143], v[198:201], v[62:65]
	v_mfma_f32_16x16x32_bf16 v[58:61], v[144:147], v[194:197], 0
	v_mfma_f32_16x16x32_bf16 v[58:61], v[148:151], v[198:201], v[58:61]
	v_mfma_f32_16x16x32_bf16 v[54:57], v[136:139], v[222:225], 0
	v_mfma_f32_16x16x32_bf16 v[54:57], v[140:143], v[226:229], v[54:57]
	v_mfma_f32_16x16x32_bf16 v[46:49], v[144:147], v[222:225], 0
	v_mfma_f32_16x16x32_bf16 v[46:49], v[148:151], v[226:229], v[46:49]
	v_mfma_f32_16x16x32_bf16 v[38:41], v[136:139], v[230:233], 0
	v_mfma_f32_16x16x32_bf16 v[38:41], v[140:143], v[234:237], v[38:41]
	v_mfma_f32_16x16x32_bf16 v[30:33], v[144:147], v[230:233], 0
	v_mfma_f32_16x16x32_bf16 v[30:33], v[148:151], v[234:237], v[30:33]
	v_mfma_f32_16x16x32_bf16 v[22:25], v[136:139], v[238:241], 0
	v_mfma_f32_16x16x32_bf16 v[22:25], v[140:143], v[242:245], v[22:25]
	v_mfma_f32_16x16x32_bf16 v[14:17], v[144:147], v[238:241], 0
	v_mfma_f32_16x16x32_bf16 v[14:17], v[148:151], v[242:245], v[14:17]
	s_setprio 0
	s_setprio 1
	v_mfma_f32_16x16x32_bf16 v[50:53], v[152:155], v[194:197], 0
	v_mfma_f32_16x16x32_bf16 v[50:53], v[180:183], v[198:201], v[50:53]
	v_mfma_f32_16x16x32_bf16 v[42:45], v[184:187], v[194:197], 0
	v_mfma_f32_16x16x32_bf16 v[42:45], v[190:193], v[198:201], v[42:45]
	v_mfma_f32_16x16x32_bf16 v[34:37], v[152:155], v[222:225], 0
	v_mfma_f32_16x16x32_bf16 v[34:37], v[180:183], v[226:229], v[34:37]
	v_mfma_f32_16x16x32_bf16 v[26:29], v[184:187], v[222:225], 0
	v_mfma_f32_16x16x32_bf16 v[26:29], v[190:193], v[226:229], v[26:29]
	v_mfma_f32_16x16x32_bf16 v[18:21], v[152:155], v[230:233], 0
	v_mfma_f32_16x16x32_bf16 v[18:21], v[180:183], v[234:237], v[18:21]
	v_mfma_f32_16x16x32_bf16 v[10:13], v[184:187], v[230:233], 0
	v_mfma_f32_16x16x32_bf16 v[10:13], v[190:193], v[234:237], v[10:13]
	v_mfma_f32_16x16x32_bf16 v[6:9], v[152:155], v[238:241], 0
	v_mfma_f32_16x16x32_bf16 v[6:9], v[180:183], v[242:245], v[6:9]
	s_setprio 2
	s_barrier
; #define PG8_STAGE(bufoff, gbase, voff) do { _Pragma("unroll") for (int _i = 0; _i < 2; ++_i) \
;         __builtin_amdgcn_global_load_lds((const unsigned*)((const char*)(gbase) + (voff)[_i]), (PG8_LAS unsigned*)(lds + (bufoff) + ldsw + _i * 8192), 16, 0, AUX_A); } while (0)
; #define PG8_LDA(dst, b, h) do { _Pragma("unroll") for (int m = 0; m < 4; ++m) _Pragma("unroll") for (int k = 0; k < 2; ++k) dst[m][k] = *(const PG8_LAS bf16x8*)(lds + PG8_SA(b, h) + aoff + m * 2048 + k * 1024); } while (0)
; #define PG8_LDB(dst, b, h) do { _Pragma("unroll") for (int n = 0; n < 2; ++n) _Pragma("unroll") for (int k = 0; k < 2; ++k) dst[n][k] = *(const PG8_LAS bf16x8*)(lds + PG8_SB(b, h) + boff + n * 2048 + k * 1024); } while (0)
; #define PG8_MMA(ai, bj, At, Bt) do { __builtin_amdgcn_s_setprio(1); _Pragma("unroll") for (int m = 0; m < 4; ++m) _Pragma("unroll") for (int n = 0; n < 2; ++n) _Pragma("unroll") for (int k = 0; k < 2; ++k) \
;         acc[ai][bj][m][n] = __builtin_amdgcn_mfma_f32_16x16x32_bf16(Bt[n][k], At[m][k], acc[ai][bj][m][n], 0, 0, 0); __builtin_amdgcn_s_setprio(0); } while (0)
; #define PG8_WAIT_V(n) asm volatile("s_waitcnt vmcnt(" #n ")" ::: "memory")
; #define PG8_WAIT_L(n) asm volatile("s_waitcnt lgkmcnt(" #n ")" ::: "memory")
; #define PG8_BAR __builtin_amdgcn_s_barrier()
; #define PG8_SCHED __builtin_amdgcn_sched_barrier(0)
; template <class Epi, class Sched, bool ALIGN_EPI = false, bool SP2 = false>
; __device__ __forceinline__ void gemm_phase(PG8_LAS unsigned char* lds, const Gemm g, const Sched& S, const Epi& E) {
;     ...
;             PG8_LDB(B0, 1, 0); PG8_LDB(B1, 1, 1); PG8_SCHED; PG8_LDA(At, 1, 0); PG8_STAGE(PG8_SA(0, 1), a2 + hstep, voffA);
;             PG8_WAIT_V(8); PG8_WAIT_L(0); PG8_BAR; PG8_MMA(0, 0, At, B0); PG8_MMA(0, 1, At, B1); PG8_BAR; PG8_SCHED;
	v_mfma_f32_16x16x32_bf16 v[2:5], v[184:187], v[238:241], 0
	v_mfma_f32_16x16x32_bf16 v[2:5], v[190:193], v[242:245], v[2:5]
	s_setprio 0
	s_add_i32 s2, 0, 0x18000
	s_add_i32 s29, 0, 0x1c000
	v_add_u32_e32 v148, s2, v99
	v_add_u32_e32 v190, s29, v99
	ds_read_b128 v[136:139], v148
	ds_read_b128 v[140:143], v148 offset:1024
	ds_read_b128 v[144:147], v148 offset:2048
	ds_read_b128 v[148:151], v148 offset:3072
	ds_read_b128 v[152:155], v190
	ds_read_b128 v[180:183], v190 offset:1024
	ds_read_b128 v[184:187], v190 offset:2048
	ds_read_b128 v[190:193], v190 offset:3072
	s_add_u32 s0, s44, 0x160000
	s_addc_u32 s1, s45, 0
	s_mov_b32 m0, s52
	v_lshl_add_u64 v[246:247], s[0:1], 0, v[162:163]
	ds_read_b128 v[194:197], v189 offset:32768
	ds_read_b128 v[198:201], v189 offset:33792
	ds_read_b128 v[222:225], v189 offset:34816
	ds_read_b128 v[226:229], v189 offset:35840
	ds_read_b128 v[230:233], v189 offset:36864
	ds_read_b128 v[234:237], v189 offset:37888
	ds_read_b128 v[238:241], v189 offset:38912
	ds_read_b128 v[242:245], v189 offset:39936
	global_load_lds_dwordx4 v[246:247], off
	v_lshl_add_u64 v[246:247], s[0:1], 0, v[158:159]
	s_mov_b32 m0, s53
	s_nop 0
	global_load_lds_dwordx4 v[246:247], off
	s_waitcnt vmcnt(8)
	s_waitcnt lgkmcnt(0)
	s_setprio 1
	s_barrier
	v_mfma_f32_16x16x32_bf16 v[128:131], v[136:139], v[194:197], v[128:131]
	v_mfma_f32_16x16x32_bf16 v[128:131], v[140:143], v[198:201], v[128:131]
	v_mfma_f32_16x16x32_bf16 v[124:127], v[144:147], v[194:197], v[124:127]
	v_mfma_f32_16x16x32_bf16 v[124:127], v[148:151], v[198:201], v[124:127]
	v_mfma_f32_16x16x32_bf16 v[120:123], v[136:139], v[222:225], v[120:123]
	v_mfma_f32_16x16x32_bf16 v[120:123], v[140:143], v[226:229], v[120:123]
	v_mfma_f32_16x16x32_bf16 v[112:115], v[144:147], v[222:225], v[112:115]
	v_mfma_f32_16x16x32_bf16 v[112:115], v[148:151], v[226:229], v[112:115]
	v_mfma_f32_16x16x32_bf16 v[104:107], v[136:139], v[230:233], v[104:107]
	v_mfma_f32_16x16x32_bf16 v[104:107], v[140:143], v[234:237], v[104:107]
	v_mfma_f32_16x16x32_bf16 v[94:97], v[144:147], v[230:233], v[94:97]
	v_mfma_f32_16x16x32_bf16 v[94:97], v[148:151], v[234:237], v[94:97]
	v_mfma_f32_16x16x32_bf16 v[86:89], v[136:139], v[238:241], v[86:89]
	v_mfma_f32_16x16x32_bf16 v[86:89], v[140:143], v[242:245], v[86:89]
	v_mfma_f32_16x16x32_bf16 v[78:81], v[144:147], v[238:241], v[78:81]
	v_mfma_f32_16x16x32_bf16 v[78:81], v[148:151], v[242:245], v[78:81]
	s_setprio 0
	s_setprio 1
	v_mfma_f32_16x16x32_bf16 v[116:119], v[152:155], v[194:197], v[116:119]
	v_mfma_f32_16x16x32_bf16 v[116:119], v[180:183], v[198:201], v[116:119]
	v_mfma_f32_16x16x32_bf16 v[108:111], v[184:187], v[194:197], v[108:111]
	v_mfma_f32_16x16x32_bf16 v[108:111], v[190:193], v[198:201], v[108:111]
	v_mfma_f32_16x16x32_bf16 v[100:103], v[152:155], v[222:225], v[100:103]
	v_mfma_f32_16x16x32_bf16 v[100:103], v[180:183], v[226:229], v[100:103]
	v_mfma_f32_16x16x32_bf16 v[90:93], v[184:187], v[222:225], v[90:93]
	v_mfma_f32_16x16x32_bf16 v[90:93], v[190:193], v[226:229], v[90:93]
	v_mfma_f32_16x16x32_bf16 v[82:85], v[152:155], v[230:233], v[82:85]
	v_mfma_f32_16x16x32_bf16 v[82:85], v[180:183], v[234:237], v[82:85]
	v_mfma_f32_16x16x32_bf16 v[74:77], v[184:187], v[230:233], v[74:77]
	v_mfma_f32_16x16x32_bf16 v[74:77], v[190:193], v[234:237], v[74:77]
	v_mfma_f32_16x16x32_bf16 v[70:73], v[152:155], v[238:241], v[70:73]
	v_mfma_f32_16x16x32_bf16 v[70:73], v[180:183], v[242:245], v[70:73]
	s_setprio 2
	s_barrier
; #define PG8_STAGE(bufoff, gbase, voff) do { _Pragma("unroll") for (int _i = 0; _i < 2; ++_i) \
;         __builtin_amdgcn_global_load_lds((const unsigned*)((const char*)(gbase) + (voff)[_i]), (PG8_LAS unsigned*)(lds + (bufoff) + ldsw + _i * 8192), 16, 0, AUX_A); } while (0)
; #define PG8_STAGEB(bufoff, gbase, voff) do { _Pragma("unroll") for (int _i = 0; _i < 2; ++_i) \
;         __builtin_amdgcn_global_load_lds((const unsigned*)((const char*)(gbase) + (voff)[_i]), (PG8_LAS unsigned*)(lds + (bufoff) + ldsw + _i * 8192), 16, 0, AUX_B); } while (0)
; #define PG8_LDA(dst, b, h) do { _Pragma("unroll") for (int m = 0; m < 4; ++m) _Pragma("unroll") for (int k = 0; k < 2; ++k) dst[m][k] = *(const PG8_LAS bf16x8*)(lds + PG8_SA(b, h) + aoff + m * 2048 + k * 1024); } while (0)
; #define PG8_MMA(ai, bj, At, Bt) do { __builtin_amdgcn_s_setprio(1); _Pragma("unroll") for (int m = 0; m < 4; ++m) _Pragma("unroll") for (int n = 0; n < 2; ++n) _Pragma("unroll") for (int k = 0; k < 2; ++k) \
;         acc[ai][bj][m][n] = __builtin_amdgcn_mfma_f32_16x16x32_bf16(Bt[n][k], At[m][k], acc[ai][bj][m][n], 0, 0, 0); __builtin_amdgcn_s_setprio(0); } while (0)
; #define PG8_WAIT_V(n) asm volatile("s_waitcnt vmcnt(" #n ")" ::: "memory")
; #define PG8_WAIT_L(n) asm volatile("s_waitcnt lgkmcnt(" #n ")" ::: "memory")
; #define PG8_BAR __builtin_amdgcn_s_barrier()
; #define PG8_SCHED __builtin_amdgcn_sched_barrier(0)
; template <class Epi, class Sched, bool ALIGN_EPI = false, bool SP2 = false>
; __device__ __forceinline__ void gemm_phase(PG8_LAS unsigned char* lds, const Gemm g, const Sched& S, const Epi& E) {
;     ...
;             PG8_LDA(At, 1, 1); PG8_STAGEB(PG8_SB(1, 0), b3, voffB); PG8_STAGEB(PG8_SB(1, 1), b3 + hstep, voffB); PG8_STAGE(PG8_SA(1, 0), a3, voffA);
;             PG8_WAIT_V(8); PG8_WAIT_L(0); PG8_BAR; PG8_MMA(1, 0, At, B0); PG8_MMA(1, 1, At, B1); PG8_BAR; PG8_SCHED;
	v_mfma_f32_16x16x32_bf16 v[66:69], v[184:187], v[238:241], v[66:69]
	v_mfma_f32_16x16x32_bf16 v[66:69], v[190:193], v[242:245], v[66:69]
	s_setprio 0
	s_add_i32 s0, s2, s49
	v_lshl_add_u64 v[168:169], v[168:169], 0, s[76:77]
	s_mov_b32 m0, s0
	ds_read_b128 v[194:197], v189 offset:49152
	ds_read_b128 v[198:201], v189 offset:50176
	ds_read_b128 v[222:225], v189 offset:51200
	ds_read_b128 v[226:229], v189 offset:52224
	ds_read_b128 v[230:233], v189 offset:53248
	ds_read_b128 v[234:237], v189 offset:54272
	ds_read_b128 v[238:241], v189 offset:55296
	ds_read_b128 v[242:245], v189 offset:56320
	global_load_lds_dwordx4 v[168:169], off
	s_add_i32 m0, s0, 0x2000
	s_add_u32 s0, s42, 0x160080
	v_lshl_add_u64 v[168:169], v[172:173], 0, s[76:77]
	s_addc_u32 s1, s43, 0
	s_add_i32 s2, s29, s49
	global_load_lds_dwordx4 v[168:169], off
	v_lshl_add_u64 v[168:169], s[0:1], 0, v[160:161]
	s_mov_b32 m0, s2
	s_nop 0
	global_load_lds_dwordx4 v[168:169], off
	v_lshl_add_u64 v[168:169], s[0:1], 0, v[156:157]
	s_add_i32 m0, s2, 0x2000
	s_nop 0
	global_load_lds_dwordx4 v[168:169], off
	v_lshl_add_u64 v[168:169], v[202:203], 0, s[76:77]
	s_mov_b32 m0, s60
	s_nop 0
	global_load_lds_dwordx4 v[168:169], off
	v_lshl_add_u64 v[168:169], v[212:213], 0, s[76:77]
	s_mov_b32 m0, s61
	s_nop 0
	global_load_lds_dwordx4 v[168:169], off
	s_waitcnt vmcnt(8)
	s_waitcnt lgkmcnt(0)
	s_setprio 1
	s_barrier
	v_mfma_f32_16x16x32_bf16 v[62:65], v[136:139], v[194:197], v[62:65]
	v_mfma_f32_16x16x32_bf16 v[62:65], v[140:143], v[198:201], v[62:65]
	v_mfma_f32_16x16x32_bf16 v[58:61], v[144:147], v[194:197], v[58:61]
	v_mfma_f32_16x16x32_bf16 v[58:61], v[148:151], v[198:201], v[58:61]
	v_mfma_f32_16x16x32_bf16 v[54:57], v[136:139], v[222:225], v[54:57]
	v_mfma_f32_16x16x32_bf16 v[54:57], v[140:143], v[226:229], v[54:57]
	v_mfma_f32_16x16x32_bf16 v[46:49], v[144:147], v[222:225], v[46:49]
	v_mfma_f32_16x16x32_bf16 v[46:49], v[148:151], v[226:229], v[46:49]
	v_mfma_f32_16x16x32_bf16 v[38:41], v[136:139], v[230:233], v[38:41]
	v_mfma_f32_16x16x32_bf16 v[38:41], v[140:143], v[234:237], v[38:41]
	v_mfma_f32_16x16x32_bf16 v[30:33], v[144:147], v[230:233], v[30:33]
	v_mfma_f32_16x16x32_bf16 v[30:33], v[148:151], v[234:237], v[30:33]
	v_mfma_f32_16x16x32_bf16 v[22:25], v[136:139], v[238:241], v[22:25]
	v_mfma_f32_16x16x32_bf16 v[22:25], v[140:143], v[242:245], v[22:25]
	v_mfma_f32_16x16x32_bf16 v[14:17], v[144:147], v[238:241], v[14:17]
	v_mfma_f32_16x16x32_bf16 v[14:17], v[148:151], v[242:245], v[14:17]
	s_setprio 0
	s_setprio 1
	v_mfma_f32_16x16x32_bf16 v[50:53], v[152:155], v[194:197], v[50:53]
	v_mfma_f32_16x16x32_bf16 v[50:53], v[180:183], v[198:201], v[50:53]
	v_mfma_f32_16x16x32_bf16 v[42:45], v[184:187], v[194:197], v[42:45]
	v_mfma_f32_16x16x32_bf16 v[42:45], v[190:193], v[198:201], v[42:45]
	v_mfma_f32_16x16x32_bf16 v[34:37], v[152:155], v[222:225], v[34:37]
	v_mfma_f32_16x16x32_bf16 v[34:37], v[180:183], v[226:229], v[34:37]
	v_mfma_f32_16x16x32_bf16 v[26:29], v[184:187], v[222:225], v[26:29]
	v_mfma_f32_16x16x32_bf16 v[26:29], v[190:193], v[226:229], v[26:29]
	v_mfma_f32_16x16x32_bf16 v[18:21], v[152:155], v[230:233], v[18:21]
	v_mfma_f32_16x16x32_bf16 v[18:21], v[180:183], v[234:237], v[18:21]
	v_mfma_f32_16x16x32_bf16 v[10:13], v[184:187], v[230:233], v[10:13]
	v_mfma_f32_16x16x32_bf16 v[10:13], v[190:193], v[234:237], v[10:13]
	v_mfma_f32_16x16x32_bf16 v[6:9], v[152:155], v[238:241], v[6:9]
	v_mfma_f32_16x16x32_bf16 v[6:9], v[180:183], v[242:245], v[6:9]
	s_setprio 2
	s_barrier
	v_mfma_f32_16x16x32_bf16 v[2:5], v[184:187], v[238:241], v[2:5]
	v_mfma_f32_16x16x32_bf16 v[2:5], v[190:193], v[242:245], v[2:5]
	s_setprio 0
	s_add_i32 s0, s83, 2
	v_lshl_add_u64 v[132:133], v[132:133], 0, s[86:87]
	v_lshl_add_u64 v[134:135], v[134:135], 0, s[86:87]
	s_cmp_ge_i32 s83, s82
	s_mov_b32 s83, s0
	s_cbranch_scc1 .Lpx_1654
